# mem-attention units: the 16 output-gate pieces prefetched before the PV loop (loop written out 4x); plus swa/pool hoists
# baseline (speedup 1.0000x reference)
.LBB0_668:
	v_lshl_add_u64 v[82:83], v[74:75], 0, v[68:69]
	v_lshl_add_u64 v[86:87], v[76:77], 0, v[68:69]
	v_lshl_add_u64 v[200:201], v[72:73], 0, v[68:69]
	v_lshl_add_u64 v[204:205], v[70:71], 0, v[68:69]
	global_load_dwordx4 v[82:85], v[82:83], off
	s_nop 0
	global_load_dwordx4 v[86:89], v[86:87], off
	s_nop 0
	global_load_dwordx4 v[200:203], v[200:201], off
	s_nop 0
	global_load_dwordx4 v[204:207], v[204:205], off
	v_add_u32_e32 v67, 0x800, v67
	v_cmp_lt_u32_e32 vcc, s38, v67
	v_add_u32_e32 v90, v80, v66
	v_add_u32_e32 v103, v81, v66
	v_add_u32_e32 v191, v79, v66
	v_add_u32_e32 v199, v78, v66
	v_add_u32_e32 v78, 0x8400, v78
	v_lshl_add_u64 v[70:71], v[70:71], 0, s[10:11]
	v_add_u32_e32 v79, 0x8400, v79
	v_lshl_add_u64 v[72:73], v[72:73], 0, s[10:11]
	v_lshl_add_u64 v[74:75], v[74:75], 0, s[10:11]
	v_add_u32_e32 v80, 0x8400, v80
	v_add_u32_e32 v81, 0x8400, v81
	v_lshl_add_u64 v[76:77], v[76:77], 0, s[10:11]
	s_or_b64 s[20:21], vcc, s[20:21]
	s_waitcnt vmcnt(3)
	ds_write_b128 v90, v[82:85]
	s_waitcnt vmcnt(2)
	ds_write_b128 v103, v[86:89]
	s_waitcnt vmcnt(1)
	ds_write_b128 v191, v[200:203]
	s_waitcnt vmcnt(0)
	ds_write_b128 v199, v[204:207]
	s_andn2_b64 exec, exec, s[20:21]
	s_cbranch_execnz .LBB0_668
	s_or_b64 exec, exec, s[20:21]
	v_mul_f32_e32 v68, 0x3d800000, v6
	v_mul_f32_e32 v69, 0x3d800000, v7
	v_max3_f32 v68, v68, s41, v69
	v_mul_f32_e32 v69, 0x3d800000, v8
	v_mul_f32_e32 v70, 0x3d800000, v9
	v_max3_f32 v68, v68, v69, v70
	v_mul_f32_e32 v69, 0x3d800000, v2
	v_mul_f32_e32 v70, 0x3d800000, v3
	v_max3_f32 v68, v68, v69, v70
	v_mul_f32_e32 v69, 0x3d800000, v4
	v_mul_f32_e32 v70, 0x3d800000, v5
	v_max3_f32 v68, v68, v69, v70
	v_mul_f32_e32 v69, 0x3d800000, v10
	v_mul_f32_e32 v70, 0x3d800000, v11
	v_max3_f32 v68, v68, v69, v70
	v_mul_f32_e32 v69, 0x3d800000, v12
	v_mul_f32_e32 v70, 0x3d800000, v13
	v_max3_f32 v68, v68, v69, v70
	v_mul_f32_e32 v69, 0x3d800000, v14
	v_mul_f32_e32 v70, 0x3d800000, v15
	v_max3_f32 v68, v68, v69, v70
	v_mul_f32_e32 v69, 0x3d800000, v16
	v_mul_f32_e32 v70, 0x3d800000, v17
	v_max3_f32 v68, v68, v69, v70
	v_mul_f32_e32 v69, 0x3d800000, v18
	v_mul_f32_e32 v70, 0x3d800000, v19
	v_max3_f32 v68, v68, v69, v70
	v_mul_f32_e32 v69, 0x3d800000, v20
	v_mul_f32_e32 v70, 0x3d800000, v21
	v_max3_f32 v68, v68, v69, v70
	v_mul_f32_e32 v69, 0x3d800000, v22
	v_mul_f32_e32 v70, 0x3d800000, v23
	v_max3_f32 v68, v68, v69, v70
	v_mul_f32_e32 v69, 0x3d800000, v24
	v_mul_f32_e32 v70, 0x3d800000, v25
	v_max3_f32 v68, v68, v69, v70
	v_mul_f32_e32 v69, 0x3d800000, v26
	v_mul_f32_e32 v70, 0x3d800000, v27
	v_max3_f32 v68, v68, v69, v70
	v_mul_f32_e32 v69, 0x3d800000, v28
	v_mul_f32_e32 v70, 0x3d800000, v29
	v_max3_f32 v68, v68, v69, v70
	v_mul_f32_e32 v69, 0x3d800000, v30
	v_mul_f32_e32 v70, 0x3d800000, v31
	v_max3_f32 v68, v68, v69, v70
	v_mul_f32_e32 v69, 0x3d800000, v32
	v_mul_f32_e32 v70, 0x3d800000, v33
	v_max3_f32 v68, v68, v69, v70
	v_mul_f32_e32 v69, 0x3d800000, v34
	v_mul_f32_e32 v70, 0x3d800000, v35
	v_max3_f32 v68, v68, v69, v70
	v_mul_f32_e32 v69, 0x3d800000, v36
	v_mul_f32_e32 v70, 0x3d800000, v37
	v_max3_f32 v68, v68, v69, v70
	v_mul_f32_e32 v69, 0x3d800000, v38
	v_mul_f32_e32 v70, 0x3d800000, v39
	v_max3_f32 v68, v68, v69, v70
	v_mul_f32_e32 v69, 0x3d800000, v40
	v_mul_f32_e32 v70, 0x3d800000, v41
	v_max3_f32 v68, v68, v69, v70
	v_mul_f32_e32 v69, 0x3d800000, v42
	v_mul_f32_e32 v70, 0x3d800000, v43
	v_max3_f32 v68, v68, v69, v70
	v_mul_f32_e32 v69, 0x3d800000, v44
	v_mul_f32_e32 v70, 0x3d800000, v45
	v_max3_f32 v68, v68, v69, v70
	v_mul_f32_e32 v69, 0x3d800000, v46
	v_mul_f32_e32 v70, 0x3d800000, v47
	v_max3_f32 v68, v68, v69, v70
	v_mul_f32_e32 v69, 0x3d800000, v48
	v_mul_f32_e32 v70, 0x3d800000, v49
	v_max3_f32 v68, v68, v69, v70
	v_mul_f32_e32 v69, 0x3d800000, v50
	v_mul_f32_e32 v70, 0x3d800000, v51
	v_max3_f32 v68, v68, v69, v70
	v_mul_f32_e32 v69, 0x3d800000, v52
	v_mul_f32_e32 v70, 0x3d800000, v53
	v_max3_f32 v68, v68, v69, v70
	v_mul_f32_e32 v69, 0x3d800000, v54
	v_mul_f32_e32 v70, 0x3d800000, v55
	v_max3_f32 v68, v68, v69, v70
	v_mul_f32_e32 v69, 0x3d800000, v56
	v_mul_f32_e32 v70, 0x3d800000, v57
	v_max3_f32 v68, v68, v69, v70
	v_mul_f32_e32 v69, 0x3d800000, v58
	v_mul_f32_e32 v70, 0x3d800000, v59
	v_max3_f32 v68, v68, v69, v70
	v_mul_f32_e32 v69, 0x3d800000, v60
	v_mul_f32_e32 v70, 0x3d800000, v61
	v_max3_f32 v68, v68, v69, v70
	v_mul_f32_e32 v69, 0x3d800000, v62
	v_mul_f32_e32 v70, 0x3d800000, v63
	v_max3_f32 v68, v68, v69, v70
	v_mul_f32_e32 v69, 0x3d800000, v64
	v_mul_f32_e32 v70, 0x3d800000, v65
	v_max3_f32 v68, v68, v69, v70
	v_and_b32_e32 v70, 64, v189
	v_xor_b32_e32 v69, 16, v189
	v_add_u32_e32 v70, 64, v70
	v_cmp_lt_i32_e32 vcc, v69, v70
	s_lshl_b32 s20, s45, 8
	v_or_b32_e32 v74, s20, v183
	v_cndmask_b32_e32 v69, v189, v69, vcc
	v_lshlrev_b32_e32 v69, 2, v69
	ds_bpermute_b32 v71, v69, v68
	s_or_b32 s0, s46, 64
	s_and_b32 s21, s36, 0xf80
	v_add_lshl_u32 v72, v182, s20, 8
	v_add_lshl_u32 v66, v177, s20, 8
	s_waitcnt lgkmcnt(0)
	v_max_f32_e32 v71, v71, v71
	v_max_f32_e32 v75, v68, v71
	v_xor_b32_e32 v68, 32, v189
	v_cmp_lt_i32_e32 vcc, v68, v70
	v_lshlrev_b32_e32 v70, 1, v74
	v_and_b32_e32 v72, 0x1fc000, v72
	v_cndmask_b32_e32 v68, v189, v68, vcc
	v_lshlrev_b32_e32 v80, 2, v68
	ds_bpermute_b32 v76, v80, v75
	v_mov_b32_e32 v73, v91
	v_and_b32_e32 v90, 0x1fc000, v66
	v_or_b32_e32 v66, s20, v181
	v_add_lshl_u32 v68, v185, s20, 8
	s_waitcnt lgkmcnt(0)
	v_max_f32_e32 v74, v76, v76
	v_max_f32_e32 v78, v75, v74
	v_fma_f32 v2, v2, s40, -v78
	v_mul_f32_e32 v2, 0x3fb8aa3b, v2
	v_exp_f32_e32 v74, v2
	v_fma_f32 v2, v3, s40, -v78
	v_mul_f32_e32 v2, 0x3fb8aa3b, v2
	v_exp_f32_e32 v75, v2
	v_fma_f32 v2, v4, s40, -v78
	v_mul_f32_e32 v2, 0x3fb8aa3b, v2
	v_exp_f32_e32 v76, v2
	v_fma_f32 v2, v5, s40, -v78
	v_mul_f32_e32 v2, 0x3fb8aa3b, v2
	v_exp_f32_e32 v77, v2
	v_fma_f32 v2, v10, s40, -v78
	v_mul_f32_e32 v2, 0x3fb8aa3b, v2
	v_exp_f32_e32 v10, v2
	v_fma_f32 v2, v11, s40, -v78
	v_mul_f32_e32 v2, 0x3fb8aa3b, v2
	v_exp_f32_e32 v11, v2
	v_fma_f32 v2, v12, s40, -v78
	v_mul_f32_e32 v2, 0x3fb8aa3b, v2
	v_exp_f32_e32 v12, v2
	v_fma_f32 v2, v13, s40, -v78
	v_mul_f32_e32 v2, 0x3fb8aa3b, v2
	v_exp_f32_e32 v13, v2
	v_fma_f32 v2, v14, s40, -v78
	v_mul_f32_e32 v2, 0x3fb8aa3b, v2
	v_exp_f32_e32 v14, v2
	v_fma_f32 v2, v15, s40, -v78
	v_mul_f32_e32 v2, 0x3fb8aa3b, v2
	v_exp_f32_e32 v15, v2
	v_fma_f32 v2, v16, s40, -v78
	v_mul_f32_e32 v2, 0x3fb8aa3b, v2
	v_exp_f32_e32 v16, v2
	v_fma_f32 v2, v17, s40, -v78
	v_mul_f32_e32 v2, 0x3fb8aa3b, v2
	v_exp_f32_e32 v17, v2
	v_fma_f32 v2, v18, s40, -v78
	v_mul_f32_e32 v2, 0x3fb8aa3b, v2
	v_exp_f32_e32 v18, v2
	v_fma_f32 v2, v19, s40, -v78
	v_mul_f32_e32 v2, 0x3fb8aa3b, v2
	v_exp_f32_e32 v19, v2
	v_fma_f32 v2, v20, s40, -v78
	v_mul_f32_e32 v2, 0x3fb8aa3b, v2
	v_exp_f32_e32 v20, v2
	v_fma_f32 v2, v21, s40, -v78
	v_mul_f32_e32 v2, 0x3fb8aa3b, v2
	v_exp_f32_e32 v21, v2
	v_fma_f32 v2, v22, s40, -v78
	v_mul_f32_e32 v2, 0x3fb8aa3b, v2
	v_exp_f32_e32 v22, v2
	v_fma_f32 v2, v23, s40, -v78
	v_mul_f32_e32 v2, 0x3fb8aa3b, v2
	v_exp_f32_e32 v23, v2
	v_fma_f32 v2, v24, s40, -v78
	v_mul_f32_e32 v2, 0x3fb8aa3b, v2
	v_exp_f32_e32 v24, v2
	v_fma_f32 v2, v25, s40, -v78
	v_mul_f32_e32 v2, 0x3fb8aa3b, v2
	v_exp_f32_e32 v25, v2
	v_fma_f32 v2, v26, s40, -v78
	v_mul_f32_e32 v2, 0x3fb8aa3b, v2
	v_exp_f32_e32 v26, v2
	v_fma_f32 v2, v27, s40, -v78
	v_mul_f32_e32 v2, 0x3fb8aa3b, v2
	v_exp_f32_e32 v27, v2
	v_fma_f32 v2, v28, s40, -v78
	v_mul_f32_e32 v2, 0x3fb8aa3b, v2
	v_exp_f32_e32 v28, v2
	v_fma_f32 v2, v29, s40, -v78
	v_mul_f32_e32 v2, 0x3fb8aa3b, v2
	v_exp_f32_e32 v29, v2
	v_fma_f32 v2, v30, s40, -v78
	v_mul_f32_e32 v2, 0x3fb8aa3b, v2
	v_exp_f32_e32 v30, v2
	v_fma_f32 v2, v31, s40, -v78
	v_mul_f32_e32 v2, 0x3fb8aa3b, v2
	v_exp_f32_e32 v31, v2
	v_fma_f32 v2, v32, s40, -v78
	v_mul_f32_e32 v2, 0x3fb8aa3b, v2
	v_exp_f32_e32 v32, v2
	v_fma_f32 v2, v33, s40, -v78
	v_mul_f32_e32 v2, 0x3fb8aa3b, v2
	v_exp_f32_e32 v33, v2
	v_fma_f32 v2, v34, s40, -v78
	v_mul_f32_e32 v2, 0x3fb8aa3b, v2
	v_exp_f32_e32 v34, v2
	v_fma_f32 v2, v35, s40, -v78
	v_mul_f32_e32 v2, 0x3fb8aa3b, v2
	v_exp_f32_e32 v35, v2
	v_fma_f32 v2, v36, s40, -v78
	v_mul_f32_e32 v2, 0x3fb8aa3b, v2
	v_exp_f32_e32 v36, v2
	v_fma_f32 v2, v37, s40, -v78
	v_mul_f32_e32 v2, 0x3fb8aa3b, v2
	v_exp_f32_e32 v37, v2
	v_fma_f32 v2, v38, s40, -v78
	v_mul_f32_e32 v2, 0x3fb8aa3b, v2
	v_exp_f32_e32 v38, v2
	v_fma_f32 v2, v39, s40, -v78
	v_mul_f32_e32 v2, 0x3fb8aa3b, v2
	v_exp_f32_e32 v39, v2
	v_fma_f32 v2, v40, s40, -v78
	v_mul_f32_e32 v2, 0x3fb8aa3b, v2
	v_exp_f32_e32 v40, v2
	v_fma_f32 v2, v41, s40, -v78
	v_mul_f32_e32 v2, 0x3fb8aa3b, v2
	v_exp_f32_e32 v41, v2
	v_fma_f32 v2, v42, s40, -v78
	v_mul_f32_e32 v2, 0x3fb8aa3b, v2
	v_exp_f32_e32 v42, v2
	v_fma_f32 v2, v43, s40, -v78
	v_mul_f32_e32 v2, 0x3fb8aa3b, v2
	v_exp_f32_e32 v43, v2
	v_fma_f32 v2, v44, s40, -v78
	v_mul_f32_e32 v2, 0x3fb8aa3b, v2
	v_exp_f32_e32 v44, v2
	v_fma_f32 v2, v45, s40, -v78
	v_mul_f32_e32 v2, 0x3fb8aa3b, v2
	v_exp_f32_e32 v45, v2
	v_fma_f32 v2, v46, s40, -v78
	v_mul_f32_e32 v2, 0x3fb8aa3b, v2
	v_exp_f32_e32 v46, v2
	v_fma_f32 v2, v47, s40, -v78
	v_mul_f32_e32 v2, 0x3fb8aa3b, v2
	v_exp_f32_e32 v47, v2
	v_fma_f32 v2, v48, s40, -v78
	v_mul_f32_e32 v2, 0x3fb8aa3b, v2
	v_exp_f32_e32 v48, v2
	v_fma_f32 v2, v49, s40, -v78
	v_mul_f32_e32 v2, 0x3fb8aa3b, v2
	v_exp_f32_e32 v49, v2
	v_fma_f32 v2, v50, s40, -v78
	v_mul_f32_e32 v2, 0x3fb8aa3b, v2
	v_exp_f32_e32 v50, v2
	v_fma_f32 v2, v51, s40, -v78
	v_mul_f32_e32 v2, 0x3fb8aa3b, v2
	v_exp_f32_e32 v51, v2
	v_fma_f32 v2, v52, s40, -v78
	v_mul_f32_e32 v2, 0x3fb8aa3b, v2
	v_exp_f32_e32 v52, v2
	v_fma_f32 v2, v53, s40, -v78
	v_mul_f32_e32 v2, 0x3fb8aa3b, v2
	v_exp_f32_e32 v53, v2
	v_fma_f32 v2, v54, s40, -v78
	v_mul_f32_e32 v2, 0x3fb8aa3b, v2
	v_exp_f32_e32 v54, v2
	v_fma_f32 v2, v55, s40, -v78
	v_mul_f32_e32 v2, 0x3fb8aa3b, v2
	v_exp_f32_e32 v55, v2
	v_fma_f32 v2, v56, s40, -v78
	v_mul_f32_e32 v2, 0x3fb8aa3b, v2
	v_exp_f32_e32 v56, v2
	v_fma_f32 v2, v57, s40, -v78
	v_mul_f32_e32 v2, 0x3fb8aa3b, v2
	v_exp_f32_e32 v57, v2
	v_fma_f32 v2, v58, s40, -v78
	v_mul_f32_e32 v2, 0x3fb8aa3b, v2
	v_exp_f32_e32 v58, v2
	v_fma_f32 v2, v59, s40, -v78
	v_mul_f32_e32 v2, 0x3fb8aa3b, v2
	v_exp_f32_e32 v59, v2
	v_fma_f32 v2, v60, s40, -v78
	v_mul_f32_e32 v2, 0x3fb8aa3b, v2
	v_exp_f32_e32 v60, v2
	v_fma_f32 v2, v61, s40, -v78
	v_mul_f32_e32 v2, 0x3fb8aa3b, v2
	v_exp_f32_e32 v61, v2
	v_fma_f32 v2, v62, s40, -v78
	v_mul_f32_e32 v2, 0x3fb8aa3b, v2
	v_fma_f32 v6, v6, s40, -v78
	v_exp_f32_e32 v62, v2
	v_fma_f32 v2, v63, s40, -v78
	v_mul_f32_e32 v6, 0x3fb8aa3b, v6
	v_fma_f32 v7, v7, s40, -v78
	v_mul_f32_e32 v2, 0x3fb8aa3b, v2
	v_exp_f32_e32 v6, v6
	v_mul_f32_e32 v7, 0x3fb8aa3b, v7
	v_fma_f32 v8, v8, s40, -v78
	v_exp_f32_e32 v63, v2
	v_fma_f32 v2, v64, s40, -v78
	v_exp_f32_e32 v7, v7
	v_mul_f32_e32 v8, 0x3fb8aa3b, v8
	v_fma_f32 v9, v9, s40, -v78
	v_mul_f32_e32 v2, 0x3fb8aa3b, v2
	v_exp_f32_e32 v8, v8
	v_mul_f32_e32 v9, 0x3fb8aa3b, v9
	v_exp_f32_e32 v64, v2
	v_fma_f32 v2, v65, s40, -v78
	v_exp_f32_e32 v9, v9
	v_mul_f32_e32 v2, 0x3fb8aa3b, v2
	v_exp_f32_e32 v65, v2
	v_add_f32_e32 v2, 0, v6
	v_add_f32_e32 v2, v7, v2
	v_add_f32_e32 v2, v8, v2
	v_add_f32_e32 v2, v9, v2
	v_add_f32_e32 v2, v74, v2
	v_add_f32_e32 v2, v75, v2
	v_add_f32_e32 v2, v76, v2
	v_add_f32_e32 v2, v77, v2
	v_add_f32_e32 v2, v10, v2
	v_add_f32_e32 v2, v11, v2
	v_add_f32_e32 v2, v12, v2
	v_add_f32_e32 v2, v13, v2
	v_add_f32_e32 v2, v14, v2
	v_add_f32_e32 v2, v15, v2
	v_add_f32_e32 v2, v16, v2
	v_add_f32_e32 v2, v17, v2
	v_add_f32_e32 v2, v18, v2
	v_add_f32_e32 v2, v19, v2
	v_add_f32_e32 v2, v20, v2
	v_add_f32_e32 v2, v21, v2
	v_add_f32_e32 v2, v22, v2
	v_add_f32_e32 v2, v23, v2
	v_add_f32_e32 v2, v24, v2
	v_add_f32_e32 v2, v25, v2
	v_add_f32_e32 v2, v26, v2
	v_add_f32_e32 v2, v27, v2
	v_add_f32_e32 v2, v28, v2
	v_add_f32_e32 v2, v29, v2
	v_add_f32_e32 v2, v30, v2
	v_add_f32_e32 v2, v31, v2
	v_add_f32_e32 v2, v32, v2
	v_add_f32_e32 v2, v33, v2
	v_add_f32_e32 v2, v34, v2
	v_add_f32_e32 v2, v35, v2
	v_add_f32_e32 v2, v36, v2
	v_add_f32_e32 v2, v37, v2
	v_add_f32_e32 v2, v38, v2
	v_add_f32_e32 v2, v39, v2
	v_add_f32_e32 v2, v40, v2
	v_add_f32_e32 v2, v41, v2
	v_add_f32_e32 v2, v42, v2
	v_add_f32_e32 v2, v43, v2
	v_add_f32_e32 v2, v44, v2
	v_add_f32_e32 v2, v45, v2
	v_add_f32_e32 v2, v46, v2
	v_add_f32_e32 v2, v47, v2
	v_add_f32_e32 v2, v48, v2
	v_add_f32_e32 v2, v49, v2
	v_add_f32_e32 v2, v50, v2
	v_add_f32_e32 v2, v51, v2
	v_add_f32_e32 v2, v52, v2
	v_add_f32_e32 v2, v53, v2
	v_add_f32_e32 v2, v54, v2
	v_add_f32_e32 v2, v55, v2
	v_add_f32_e32 v2, v56, v2
	v_add_f32_e32 v2, v57, v2
	v_add_f32_e32 v2, v58, v2
	v_add_f32_e32 v2, v59, v2
	v_add_f32_e32 v2, v60, v2
	v_add_f32_e32 v2, v61, v2
	v_add_f32_e32 v2, v62, v2
	v_add_f32_e32 v2, v63, v2
	v_add_f32_e32 v2, v64, v2
	v_add_f32_e32 v2, v65, v2
	ds_bpermute_b32 v3, v69, v2
	v_or_b32_e32 v4, s20, v186
	v_lshlrev_b32_e32 v78, 1, v4
	v_or_b32_e32 v4, s20, v173
	v_mov_b32_e32 v83, v91
	s_waitcnt lgkmcnt(0)
	v_add_f32_e32 v2, v2, v3
	ds_bpermute_b32 v3, v80, v2
	v_lshlrev_b32_e32 v80, 1, v4
	v_add_lshl_u32 v4, v187, s20, 8
	v_and_b32_e32 v82, 0x1fc000, v4
	v_lshlrev_b32_e32 v66, 1, v66
	s_waitcnt lgkmcnt(0)
	v_add_f32_e32 v2, v2, v3
	v_div_scale_f32 v3, s[22:23], v2, v2, 1.0
	v_rcp_f32_e32 v5, v3
	s_ashr_i32 s22, s44, 7
	s_ashr_i32 s23, s22, 31
	s_lshl_b64 s[22:23], s[22:23], 20
	v_fma_f32 v4, -v3, v5, 1.0
	v_fmac_f32_e32 v5, v4, v5
	v_div_scale_f32 v4, vcc, 1.0, v2, 1.0
	v_mul_f32_e32 v84, v4, v5
	v_fma_f32 v85, -v3, v84, v4
	v_fmac_f32_e32 v84, v85, v5
	v_fma_f32 v3, -v3, v84, v4
	v_div_fmas_f32 v3, v3, v5, v84
	v_div_fixup_f32 v84, v3, v2, 1.0
	v_pk_mul_f32 v[2:3], v[6:7], v[84:85] op_sel_hi:[1,0]
	v_pk_mul_f32 v[4:5], v[8:9], v[84:85] op_sel_hi:[1,0]
	v_cvt_pk_bf16_f32 v2, v2, v3
	v_cvt_pk_bf16_f32 v3, v4, v5
	v_pk_mul_f32 v[4:5], v[74:75], v[84:85] op_sel_hi:[1,0]
	v_pk_mul_f32 v[6:7], v[76:77], v[84:85] op_sel_hi:[1,0]
	v_cvt_pk_bf16_f32 v4, v4, v5
	v_cvt_pk_bf16_f32 v5, v6, v7
	v_pk_mul_f32 v[6:7], v[10:11], v[84:85] op_sel_hi:[1,0]
	v_pk_mul_f32 v[8:9], v[12:13], v[84:85] op_sel_hi:[1,0]
	v_cvt_pk_bf16_f32 v6, v6, v7
	v_cvt_pk_bf16_f32 v7, v8, v9
	v_pk_mul_f32 v[8:9], v[14:15], v[84:85] op_sel_hi:[1,0]
	v_pk_mul_f32 v[10:11], v[16:17], v[84:85] op_sel_hi:[1,0]
	v_cvt_pk_bf16_f32 v8, v8, v9
	v_cvt_pk_bf16_f32 v9, v10, v11
	v_pk_mul_f32 v[10:11], v[18:19], v[84:85] op_sel_hi:[1,0]
	v_pk_mul_f32 v[12:13], v[20:21], v[84:85] op_sel_hi:[1,0]
	v_cvt_pk_bf16_f32 v10, v10, v11
	v_cvt_pk_bf16_f32 v11, v12, v13
	v_pk_mul_f32 v[12:13], v[22:23], v[84:85] op_sel_hi:[1,0]
	v_pk_mul_f32 v[14:15], v[24:25], v[84:85] op_sel_hi:[1,0]
	v_cvt_pk_bf16_f32 v12, v12, v13
	v_cvt_pk_bf16_f32 v13, v14, v15
	v_pk_mul_f32 v[14:15], v[26:27], v[84:85] op_sel_hi:[1,0]
	v_pk_mul_f32 v[16:17], v[28:29], v[84:85] op_sel_hi:[1,0]
	v_cvt_pk_bf16_f32 v14, v14, v15
	v_cvt_pk_bf16_f32 v15, v16, v17
	v_pk_mul_f32 v[16:17], v[30:31], v[84:85] op_sel_hi:[1,0]
	v_pk_mul_f32 v[18:19], v[32:33], v[84:85] op_sel_hi:[1,0]
	v_cvt_pk_bf16_f32 v16, v16, v17
	v_cvt_pk_bf16_f32 v17, v18, v19
	v_pk_mul_f32 v[18:19], v[34:35], v[84:85] op_sel_hi:[1,0]
	v_pk_mul_f32 v[20:21], v[36:37], v[84:85] op_sel_hi:[1,0]
	v_cvt_pk_bf16_f32 v18, v18, v19
	v_cvt_pk_bf16_f32 v19, v20, v21
	v_pk_mul_f32 v[20:21], v[38:39], v[84:85] op_sel_hi:[1,0]
	v_pk_mul_f32 v[22:23], v[40:41], v[84:85] op_sel_hi:[1,0]
	v_cvt_pk_bf16_f32 v20, v20, v21
	v_cvt_pk_bf16_f32 v21, v22, v23
	v_pk_mul_f32 v[22:23], v[42:43], v[84:85] op_sel_hi:[1,0]
	v_pk_mul_f32 v[24:25], v[44:45], v[84:85] op_sel_hi:[1,0]
	v_cvt_pk_bf16_f32 v22, v22, v23
	v_cvt_pk_bf16_f32 v23, v24, v25
	v_pk_mul_f32 v[24:25], v[46:47], v[84:85] op_sel_hi:[1,0]
	v_pk_mul_f32 v[26:27], v[48:49], v[84:85] op_sel_hi:[1,0]
	v_cvt_pk_bf16_f32 v24, v24, v25
	v_cvt_pk_bf16_f32 v25, v26, v27
	v_pk_mul_f32 v[26:27], v[50:51], v[84:85] op_sel_hi:[1,0]
	v_pk_mul_f32 v[28:29], v[52:53], v[84:85] op_sel_hi:[1,0]
	v_cvt_pk_bf16_f32 v26, v26, v27
	v_cvt_pk_bf16_f32 v27, v28, v29
	v_pk_mul_f32 v[28:29], v[54:55], v[84:85] op_sel_hi:[1,0]
	v_pk_mul_f32 v[30:31], v[56:57], v[84:85] op_sel_hi:[1,0]
	s_add_u32 s24, s22, 0xf000400
	v_cvt_pk_bf16_f32 v28, v28, v29
	v_cvt_pk_bf16_f32 v29, v30, v31
	v_pk_mul_f32 v[30:31], v[58:59], v[84:85] op_sel_hi:[1,0]
	v_pk_mul_f32 v[32:33], v[60:61], v[84:85] op_sel_hi:[1,0]
	s_addc_u32 s25, s23, 0
	s_add_i32 s21, s21, s43
	v_cvt_pk_bf16_f32 v30, v30, v31
	v_cvt_pk_bf16_f32 v31, v32, v33
	v_pk_mul_f32 v[32:33], v[62:63], v[84:85] op_sel_hi:[1,0]
	v_pk_mul_f32 v[34:35], v[64:65], v[84:85] op_sel_hi:[1,0]
	v_add_u32_e32 v40, s21, v180
	v_cvt_pk_bf16_f32 v32, v32, v33
	v_cvt_pk_bf16_f32 v33, v34, v35
	v_lshlrev_b32_e32 v34, 6, v190
	v_mad_i64_i32 v[46:47], s[26:27], v40, s39, v[104:105]
	v_lshlrev_b32_e32 v40, 2, v40
	v_and_b32_e32 v50, 0x3c0, v34
	v_lshlrev_b32_e32 v34, 2, v190
	v_lshl_add_u64 v[38:39], s[24:25], 0, v[72:73]
	v_and_b32_e32 v52, 32, v40
	s_add_u32 s22, s22, 0xf000000
	v_and_b32_e32 v51, 32, v34
	v_lshl_add_u64 v[34:35], s[24:25], 0, v[90:91]
	v_and_or_b32 v38, v70, 24, v38
	v_add_u32_e32 v90, v184, v52
	s_addc_u32 s23, s23, 0
	v_mov_b32_e32 v67, v91
	v_mov_b32_e32 v71, v91
	v_and_b32_e32 v68, 0x1fc000, v68
	v_mov_b32_e32 v69, v91
	v_mov_b32_e32 v79, v91
	v_mov_b32_e32 v81, v91
	v_lshl_add_u64 v[38:39], v[38:39], 0, v[90:91]
	v_lshl_add_u64 v[48:49], s[22:23], 0, v[82:83]
	v_add_u32_e32 v90, v188, v52
	s_mov_b32 s20, 16
	v_lshl_add_u64 v[36:37], v[46:47], 0, v[66:67]
	v_lshl_add_u64 v[40:41], v[46:47], 0, v[70:71]
	v_lshl_add_u64 v[42:43], s[22:23], 0, v[68:69]
	v_lshl_add_u64 v[44:45], v[46:47], 0, v[78:79]
	v_lshl_add_u64 v[46:47], v[46:47], 0, v[80:81]
	v_lshl_add_u64 v[48:49], v[48:49], 0, v[90:91]
	v_mov_b32_e32 v52, v107
	v_lshl_add_u64 v[234:235], s[92:93], 0, v[46:47]
	global_load_dwordx2 v[200:201], v[234:235], off
	global_load_dwordx2 v[208:209], v[234:235], off offset:128
	global_load_dwordx2 v[216:217], v[234:235], off offset:256
	global_load_dwordx2 v[224:225], v[234:235], off offset:384
	v_lshl_add_u64 v[234:235], s[92:93], 0, v[44:45]
	global_load_dwordx2 v[202:203], v[234:235], off
	global_load_dwordx2 v[210:211], v[234:235], off offset:128
	global_load_dwordx2 v[218:219], v[234:235], off offset:256
	global_load_dwordx2 v[226:227], v[234:235], off offset:384
	v_lshl_add_u64 v[234:235], s[92:93], 0, v[40:41]
	global_load_dwordx2 v[204:205], v[234:235], off
	global_load_dwordx2 v[212:213], v[234:235], off offset:128
	global_load_dwordx2 v[220:221], v[234:235], off offset:256
	global_load_dwordx2 v[228:229], v[234:235], off offset:384
	v_lshl_add_u64 v[234:235], s[92:93], 0, v[36:37]
	global_load_dwordx2 v[206:207], v[234:235], off
	global_load_dwordx2 v[214:215], v[234:235], off offset:128
	global_load_dwordx2 v[222:223], v[234:235], off offset:256
	global_load_dwordx2 v[230:231], v[234:235], off offset:384
	s_barrier
.LBB0_670:
	v_add_u32_e32 v53, v52, v174
	ds_read2_b64 v[54:57], v53 offset1:4
	ds_read2_b64 v[58:61], v53 offset0:8 offset1:12
	s_waitcnt lgkmcnt(1)
	v_mfma_f32_16x16x32_bf16 v[54:57], v[54:57], v[2:5], 0
	s_waitcnt lgkmcnt(0)
	v_mfma_f32_16x16x32_bf16 v[54:57], v[58:61], v[6:9], v[54:57]
	ds_read2_b64 v[58:61], v53 offset0:16 offset1:20
	s_waitcnt lgkmcnt(0)
	v_mfma_f32_16x16x32_bf16 v[54:57], v[58:61], v[10:13], v[54:57]
	ds_read2_b64 v[58:61], v53 offset0:24 offset1:28
	s_waitcnt lgkmcnt(0)
	v_mfma_f32_16x16x32_bf16 v[54:57], v[58:61], v[14:17], v[54:57]
	ds_read2_b64 v[58:61], v53 offset0:32 offset1:36
	s_waitcnt lgkmcnt(0)
	v_mfma_f32_16x16x32_bf16 v[54:57], v[58:61], v[18:21], v[54:57]
	ds_read2_b64 v[58:61], v53 offset0:40 offset1:44
	s_waitcnt lgkmcnt(0)
	v_mfma_f32_16x16x32_bf16 v[54:57], v[58:61], v[22:25], v[54:57]
	ds_read2_b64 v[58:61], v53 offset0:48 offset1:52
	s_waitcnt lgkmcnt(0)
	v_mfma_f32_16x16x32_bf16 v[54:57], v[58:61], v[26:29], v[54:57]
	ds_read2_b64 v[58:61], v53 offset0:56 offset1:60
	s_waitcnt lgkmcnt(0)
	v_mfma_f32_16x16x32_bf16 v[54:57], v[58:61], v[30:33], v[54:57]
	v_lshl_add_u64 v[58:59], s[92:93], 0, v[46:47]
	s_waitcnt vmcnt(0)
	v_mov_b32_e32 v70, v200
	v_mov_b32_e32 v71, v201
	v_add_u32_e32 v66, 0x2000, v53
	ds_read2_b64 v[58:61], v66 offset0:32 offset1:36
	ds_read2_b64 v[62:65], v66 offset0:40 offset1:44
	v_lshl_add_u64 v[72:73], s[92:93], 0, v[48:49]
	s_waitcnt lgkmcnt(1)
	v_mfma_f32_16x16x32_bf16 v[58:61], v[58:61], v[2:5], 0
	s_waitcnt lgkmcnt(0)
	v_mfma_f32_16x16x32_bf16 v[58:61], v[62:65], v[6:9], v[58:61]
	ds_read2_b64 v[62:65], v66 offset0:48 offset1:52
	s_waitcnt lgkmcnt(0)
	v_mfma_f32_16x16x32_bf16 v[58:61], v[62:65], v[10:13], v[58:61]
	ds_read2_b64 v[62:65], v66 offset0:56 offset1:60
	s_waitcnt lgkmcnt(0)
	v_mfma_f32_16x16x32_bf16 v[58:61], v[62:65], v[14:17], v[58:61]
	ds_read2_b64 v[62:65], v66 offset0:64 offset1:68
	s_waitcnt lgkmcnt(0)
	v_mfma_f32_16x16x32_bf16 v[58:61], v[62:65], v[18:21], v[58:61]
	ds_read2_b64 v[62:65], v66 offset0:72 offset1:76
	s_waitcnt lgkmcnt(0)
	v_mfma_f32_16x16x32_bf16 v[58:61], v[62:65], v[22:25], v[58:61]
	ds_read2_b64 v[62:65], v66 offset0:80 offset1:84
	ds_read2_b64 v[66:69], v66 offset0:88 offset1:92
	s_waitcnt lgkmcnt(1)
	v_mfma_f32_16x16x32_bf16 v[58:61], v[62:65], v[26:29], v[58:61]
	v_lshlrev_b32_e32 v62, 16, v70
	v_and_b32_e32 v63, 0xffff0000, v70
	v_lshlrev_b32_e32 v64, 16, v71
	v_and_b32_e32 v65, 0xffff0000, v71
	v_pk_mul_f32 v[54:55], v[54:55], v[62:63]
	v_pk_mul_f32 v[56:57], v[56:57], v[64:65]
	v_cvt_pk_bf16_f32 v54, v54, v55
	v_cvt_pk_bf16_f32 v55, v56, v57
	global_store_dwordx2 v[72:73], v[54:55], off
	s_waitcnt lgkmcnt(0)
	v_mfma_f32_16x16x32_bf16 v[54:57], v[66:69], v[30:33], v[58:61]
	s_nop 2
	v_lshl_add_u64 v[58:59], s[92:93], 0, v[44:45]
	v_mov_b32_e32 v74, v202
	v_mov_b32_e32 v75, v203
	v_add_u32_e32 v76, 0x4000, v53
	ds_read2_b64 v[58:61], v76 offset0:64 offset1:68
	ds_read2_b64 v[62:65], v76 offset0:72 offset1:76
	ds_read2_b64 v[66:69], v76 offset0:80 offset1:84
	s_waitcnt lgkmcnt(2)
	v_mfma_f32_16x16x32_bf16 v[58:61], v[58:61], v[2:5], 0
	ds_read2_b64 v[70:73], v76 offset0:112 offset1:116
	v_add_u32_e32 v77, s0, v174
	v_subrev_u32_e32 v78, 32, v77
	s_waitcnt lgkmcnt(2)
	v_mfma_f32_16x16x32_bf16 v[58:61], v[62:65], v[6:9], v[58:61]
	ds_read2_b64 v[62:65], v76 offset0:88 offset1:92
	s_waitcnt lgkmcnt(2)
	v_mfma_f32_16x16x32_bf16 v[58:61], v[66:69], v[10:13], v[58:61]
	ds_read2_b64 v[66:69], v76 offset0:96 offset1:100
	s_waitcnt lgkmcnt(1)
	v_mfma_f32_16x16x32_bf16 v[58:61], v[62:65], v[14:17], v[58:61]
	ds_read2_b64 v[62:65], v76 offset0:104 offset1:108
	s_waitcnt lgkmcnt(1)
	v_mfma_f32_16x16x32_bf16 v[58:61], v[66:69], v[18:21], v[58:61]
	ds_read2_b64 v[66:69], v76 offset0:120 offset1:124
	v_and_or_b32 v76, v78, 56, v50
	v_bitop3_b32 v90, v76, s33, v51 bitop3:0xde
	s_waitcnt lgkmcnt(1)
	v_mfma_f32_16x16x32_bf16 v[58:61], v[62:65], v[22:25], v[58:61]
	v_lshl_add_u64 v[62:63], v[42:43], 0, v[90:91]
	v_lshl_add_u64 v[62:63], s[92:93], 0, v[62:63]
	v_lshlrev_b32_e32 v64, 16, v74
	v_mfma_f32_16x16x32_bf16 v[58:61], v[70:73], v[26:29], v[58:61]
	v_and_b32_e32 v65, 0xffff0000, v74
	v_lshlrev_b32_e32 v70, 16, v75
	v_and_b32_e32 v71, 0xffff0000, v75
	v_pk_mul_f32 v[54:55], v[54:55], v[64:65]
	v_pk_mul_f32 v[56:57], v[56:57], v[70:71]
	v_cvt_pk_bf16_f32 v54, v54, v55
	v_cvt_pk_bf16_f32 v55, v56, v57
	global_store_dwordx2 v[62:63], v[54:55], off
	s_waitcnt lgkmcnt(0)
	v_mfma_f32_16x16x32_bf16 v[54:57], v[66:69], v[30:33], v[58:61]
	s_nop 2
	v_lshl_add_u64 v[58:59], s[92:93], 0, v[40:41]
	v_mov_b32_e32 v70, v204
	v_mov_b32_e32 v71, v205
	v_add_u32_e32 v53, 0x6000, v53
	ds_read2_b64 v[58:61], v53 offset0:96 offset1:100
	ds_read2_b64 v[62:65], v53 offset0:104 offset1:108
	ds_read2_b64 v[66:69], v53 offset0:152 offset1:156
	v_lshl_add_u64 v[72:73], s[92:93], 0, v[38:39]
	s_waitcnt lgkmcnt(2)
	v_mfma_f32_16x16x32_bf16 v[58:61], v[58:61], v[2:5], 0
	s_waitcnt lgkmcnt(1)
	v_mfma_f32_16x16x32_bf16 v[58:61], v[62:65], v[6:9], v[58:61]
	ds_read2_b64 v[62:65], v53 offset0:112 offset1:116
	s_waitcnt lgkmcnt(0)
	v_mfma_f32_16x16x32_bf16 v[58:61], v[62:65], v[10:13], v[58:61]
	ds_read2_b64 v[62:65], v53 offset0:120 offset1:124
	s_waitcnt lgkmcnt(0)
	v_mfma_f32_16x16x32_bf16 v[58:61], v[62:65], v[14:17], v[58:61]
	ds_read2_b64 v[62:65], v53 offset0:128 offset1:132
	s_waitcnt lgkmcnt(0)
	v_mfma_f32_16x16x32_bf16 v[58:61], v[62:65], v[18:21], v[58:61]
	ds_read2_b64 v[62:65], v53 offset0:136 offset1:140
	s_waitcnt lgkmcnt(0)
	v_mfma_f32_16x16x32_bf16 v[58:61], v[62:65], v[22:25], v[58:61]
	ds_read2_b64 v[62:65], v53 offset0:144 offset1:148
	s_waitcnt lgkmcnt(0)
	v_mfma_f32_16x16x32_bf16 v[58:61], v[62:65], v[26:29], v[58:61]
	v_lshlrev_b32_e32 v62, 16, v70
	v_and_b32_e32 v63, 0xffff0000, v70
	v_lshlrev_b32_e32 v64, 16, v71
	v_and_b32_e32 v65, 0xffff0000, v71
	v_pk_mul_f32 v[54:55], v[54:55], v[62:63]
	v_pk_mul_f32 v[56:57], v[56:57], v[64:65]
	v_cvt_pk_bf16_f32 v54, v54, v55
	v_cvt_pk_bf16_f32 v55, v56, v57
	global_store_dwordx2 v[72:73], v[54:55], off
	v_mfma_f32_16x16x32_bf16 v[54:57], v[66:69], v[30:33], v[58:61]
	s_nop 2
	v_lshl_add_u64 v[58:59], s[92:93], 0, v[36:37]
	v_mov_b32_e32 v58, v206
	v_mov_b32_e32 v59, v207
	v_add_u32_e32 v53, 32, v77
	v_and_or_b32 v53, v53, 56, v50
	v_xad_u32 v90, v53, v51, s33
	s_addk_i32 s0, 0x80
	s_add_i32 s20, s20, -4
	v_lshl_add_u64 v[60:61], v[34:35], 0, v[90:91]
	v_lshl_add_u64 v[36:37], v[36:37], 0, s[18:19]
	v_lshl_add_u64 v[38:39], v[38:39], 0, s[14:15]
	v_lshl_add_u64 v[40:41], v[40:41], 0, s[18:19]
	v_lshl_add_u64 v[42:43], v[42:43], 0, s[14:15]
	v_lshl_add_u64 v[44:45], v[44:45], 0, s[18:19]
	v_lshl_add_u64 v[46:47], v[46:47], 0, s[18:19]
	v_lshl_add_u64 v[48:49], v[48:49], 0, s[14:15]
	v_add_u32_e32 v52, 0x8400, v52
	s_cmp_lg_u32 s20, 0
	v_lshl_add_u64 v[34:35], v[34:35], 0, s[14:15]
	v_lshl_add_u64 v[60:61], s[92:93], 0, v[60:61]
	v_lshlrev_b32_e32 v62, 16, v58
	v_and_b32_e32 v63, 0xffff0000, v58
	v_lshlrev_b32_e32 v58, 16, v59
	v_and_b32_e32 v59, 0xffff0000, v59
	v_pk_mul_f32 v[54:55], v[54:55], v[62:63]
	v_pk_mul_f32 v[56:57], v[56:57], v[58:59]
	v_cvt_pk_bf16_f32 v54, v54, v55
	v_cvt_pk_bf16_f32 v55, v56, v57
	global_store_dwordx2 v[60:61], v[54:55], off
	v_add_u32_e32 v53, v52, v174
	ds_read2_b64 v[54:57], v53 offset1:4
	ds_read2_b64 v[58:61], v53 offset0:8 offset1:12
	s_waitcnt lgkmcnt(1)
	v_mfma_f32_16x16x32_bf16 v[54:57], v[54:57], v[2:5], 0
	s_waitcnt lgkmcnt(0)
	v_mfma_f32_16x16x32_bf16 v[54:57], v[58:61], v[6:9], v[54:57]
	ds_read2_b64 v[58:61], v53 offset0:16 offset1:20
	s_waitcnt lgkmcnt(0)
	v_mfma_f32_16x16x32_bf16 v[54:57], v[58:61], v[10:13], v[54:57]
	ds_read2_b64 v[58:61], v53 offset0:24 offset1:28
	s_waitcnt lgkmcnt(0)
	v_mfma_f32_16x16x32_bf16 v[54:57], v[58:61], v[14:17], v[54:57]
	ds_read2_b64 v[58:61], v53 offset0:32 offset1:36
	s_waitcnt lgkmcnt(0)
	v_mfma_f32_16x16x32_bf16 v[54:57], v[58:61], v[18:21], v[54:57]
	ds_read2_b64 v[58:61], v53 offset0:40 offset1:44
	s_waitcnt lgkmcnt(0)
	v_mfma_f32_16x16x32_bf16 v[54:57], v[58:61], v[22:25], v[54:57]
	ds_read2_b64 v[58:61], v53 offset0:48 offset1:52
	s_waitcnt lgkmcnt(0)
	v_mfma_f32_16x16x32_bf16 v[54:57], v[58:61], v[26:29], v[54:57]
	ds_read2_b64 v[58:61], v53 offset0:56 offset1:60
	s_waitcnt lgkmcnt(0)
	v_mfma_f32_16x16x32_bf16 v[54:57], v[58:61], v[30:33], v[54:57]
	v_lshl_add_u64 v[58:59], s[92:93], 0, v[46:47]
	v_mov_b32_e32 v70, v208
	v_mov_b32_e32 v71, v209
	v_add_u32_e32 v66, 0x2000, v53
	ds_read2_b64 v[58:61], v66 offset0:32 offset1:36
	ds_read2_b64 v[62:65], v66 offset0:40 offset1:44
	v_lshl_add_u64 v[72:73], s[92:93], 0, v[48:49]
	s_waitcnt lgkmcnt(1)
	v_mfma_f32_16x16x32_bf16 v[58:61], v[58:61], v[2:5], 0
	s_waitcnt lgkmcnt(0)
	v_mfma_f32_16x16x32_bf16 v[58:61], v[62:65], v[6:9], v[58:61]
	ds_read2_b64 v[62:65], v66 offset0:48 offset1:52
	s_waitcnt lgkmcnt(0)
	v_mfma_f32_16x16x32_bf16 v[58:61], v[62:65], v[10:13], v[58:61]
	ds_read2_b64 v[62:65], v66 offset0:56 offset1:60
	s_waitcnt lgkmcnt(0)
	v_mfma_f32_16x16x32_bf16 v[58:61], v[62:65], v[14:17], v[58:61]
	ds_read2_b64 v[62:65], v66 offset0:64 offset1:68
	s_waitcnt lgkmcnt(0)
	v_mfma_f32_16x16x32_bf16 v[58:61], v[62:65], v[18:21], v[58:61]
	ds_read2_b64 v[62:65], v66 offset0:72 offset1:76
	s_waitcnt lgkmcnt(0)
	v_mfma_f32_16x16x32_bf16 v[58:61], v[62:65], v[22:25], v[58:61]
	ds_read2_b64 v[62:65], v66 offset0:80 offset1:84
	ds_read2_b64 v[66:69], v66 offset0:88 offset1:92
	s_waitcnt lgkmcnt(1)
	v_mfma_f32_16x16x32_bf16 v[58:61], v[62:65], v[26:29], v[58:61]
	v_lshlrev_b32_e32 v62, 16, v70
	v_and_b32_e32 v63, 0xffff0000, v70
	v_lshlrev_b32_e32 v64, 16, v71
	v_and_b32_e32 v65, 0xffff0000, v71
	v_pk_mul_f32 v[54:55], v[54:55], v[62:63]
	v_pk_mul_f32 v[56:57], v[56:57], v[64:65]
	v_cvt_pk_bf16_f32 v54, v54, v55
	v_cvt_pk_bf16_f32 v55, v56, v57
	global_store_dwordx2 v[72:73], v[54:55], off
	s_waitcnt lgkmcnt(0)
	v_mfma_f32_16x16x32_bf16 v[54:57], v[66:69], v[30:33], v[58:61]
	s_nop 2
	v_lshl_add_u64 v[58:59], s[92:93], 0, v[44:45]
	v_mov_b32_e32 v74, v210
	v_mov_b32_e32 v75, v211
	v_add_u32_e32 v76, 0x4000, v53
	ds_read2_b64 v[58:61], v76 offset0:64 offset1:68
	ds_read2_b64 v[62:65], v76 offset0:72 offset1:76
	ds_read2_b64 v[66:69], v76 offset0:80 offset1:84
	s_waitcnt lgkmcnt(2)
	v_mfma_f32_16x16x32_bf16 v[58:61], v[58:61], v[2:5], 0
	ds_read2_b64 v[70:73], v76 offset0:112 offset1:116
	v_add_u32_e32 v77, s0, v174
	v_subrev_u32_e32 v78, 32, v77
	s_waitcnt lgkmcnt(2)
	v_mfma_f32_16x16x32_bf16 v[58:61], v[62:65], v[6:9], v[58:61]
	ds_read2_b64 v[62:65], v76 offset0:88 offset1:92
	s_waitcnt lgkmcnt(2)
	v_mfma_f32_16x16x32_bf16 v[58:61], v[66:69], v[10:13], v[58:61]
	ds_read2_b64 v[66:69], v76 offset0:96 offset1:100
	s_waitcnt lgkmcnt(1)
	v_mfma_f32_16x16x32_bf16 v[58:61], v[62:65], v[14:17], v[58:61]
	ds_read2_b64 v[62:65], v76 offset0:104 offset1:108
	s_waitcnt lgkmcnt(1)
	v_mfma_f32_16x16x32_bf16 v[58:61], v[66:69], v[18:21], v[58:61]
	ds_read2_b64 v[66:69], v76 offset0:120 offset1:124
	v_and_or_b32 v76, v78, 56, v50
	v_bitop3_b32 v90, v76, s33, v51 bitop3:0xde
	s_waitcnt lgkmcnt(1)
	v_mfma_f32_16x16x32_bf16 v[58:61], v[62:65], v[22:25], v[58:61]
	v_lshl_add_u64 v[62:63], v[42:43], 0, v[90:91]
	v_lshl_add_u64 v[62:63], s[92:93], 0, v[62:63]
	v_lshlrev_b32_e32 v64, 16, v74
	v_mfma_f32_16x16x32_bf16 v[58:61], v[70:73], v[26:29], v[58:61]
	v_and_b32_e32 v65, 0xffff0000, v74
	v_lshlrev_b32_e32 v70, 16, v75
	v_and_b32_e32 v71, 0xffff0000, v75
	v_pk_mul_f32 v[54:55], v[54:55], v[64:65]
	v_pk_mul_f32 v[56:57], v[56:57], v[70:71]
	v_cvt_pk_bf16_f32 v54, v54, v55
	v_cvt_pk_bf16_f32 v55, v56, v57
	global_store_dwordx2 v[62:63], v[54:55], off
	s_waitcnt lgkmcnt(0)
	v_mfma_f32_16x16x32_bf16 v[54:57], v[66:69], v[30:33], v[58:61]
	s_nop 2
	v_lshl_add_u64 v[58:59], s[92:93], 0, v[40:41]
	v_mov_b32_e32 v70, v212
	v_mov_b32_e32 v71, v213
	v_add_u32_e32 v53, 0x6000, v53
	ds_read2_b64 v[58:61], v53 offset0:96 offset1:100
	ds_read2_b64 v[62:65], v53 offset0:104 offset1:108
	ds_read2_b64 v[66:69], v53 offset0:152 offset1:156
	v_lshl_add_u64 v[72:73], s[92:93], 0, v[38:39]
	s_waitcnt lgkmcnt(2)
	v_mfma_f32_16x16x32_bf16 v[58:61], v[58:61], v[2:5], 0
	s_waitcnt lgkmcnt(1)
	v_mfma_f32_16x16x32_bf16 v[58:61], v[62:65], v[6:9], v[58:61]
	ds_read2_b64 v[62:65], v53 offset0:112 offset1:116
	s_waitcnt lgkmcnt(0)
	v_mfma_f32_16x16x32_bf16 v[58:61], v[62:65], v[10:13], v[58:61]
	ds_read2_b64 v[62:65], v53 offset0:120 offset1:124
	s_waitcnt lgkmcnt(0)
	v_mfma_f32_16x16x32_bf16 v[58:61], v[62:65], v[14:17], v[58:61]
	ds_read2_b64 v[62:65], v53 offset0:128 offset1:132
	s_waitcnt lgkmcnt(0)
	v_mfma_f32_16x16x32_bf16 v[58:61], v[62:65], v[18:21], v[58:61]
	ds_read2_b64 v[62:65], v53 offset0:136 offset1:140
	s_waitcnt lgkmcnt(0)
	v_mfma_f32_16x16x32_bf16 v[58:61], v[62:65], v[22:25], v[58:61]
	ds_read2_b64 v[62:65], v53 offset0:144 offset1:148
	s_waitcnt lgkmcnt(0)
	v_mfma_f32_16x16x32_bf16 v[58:61], v[62:65], v[26:29], v[58:61]
	v_lshlrev_b32_e32 v62, 16, v70
	v_and_b32_e32 v63, 0xffff0000, v70
	v_lshlrev_b32_e32 v64, 16, v71
	v_and_b32_e32 v65, 0xffff0000, v71
	v_pk_mul_f32 v[54:55], v[54:55], v[62:63]
	v_pk_mul_f32 v[56:57], v[56:57], v[64:65]
	v_cvt_pk_bf16_f32 v54, v54, v55
	v_cvt_pk_bf16_f32 v55, v56, v57
	global_store_dwordx2 v[72:73], v[54:55], off
	v_mfma_f32_16x16x32_bf16 v[54:57], v[66:69], v[30:33], v[58:61]
	s_nop 2
	v_lshl_add_u64 v[58:59], s[92:93], 0, v[36:37]
	v_mov_b32_e32 v58, v214
	v_mov_b32_e32 v59, v215
	v_add_u32_e32 v53, 32, v77
	v_and_or_b32 v53, v53, 56, v50
	v_xad_u32 v90, v53, v51, s33
	s_addk_i32 s0, 0x80
	s_add_i32 s20, s20, -4
	v_lshl_add_u64 v[60:61], v[34:35], 0, v[90:91]
	v_lshl_add_u64 v[36:37], v[36:37], 0, s[18:19]
	v_lshl_add_u64 v[38:39], v[38:39], 0, s[14:15]
	v_lshl_add_u64 v[40:41], v[40:41], 0, s[18:19]
	v_lshl_add_u64 v[42:43], v[42:43], 0, s[14:15]
	v_lshl_add_u64 v[44:45], v[44:45], 0, s[18:19]
	v_lshl_add_u64 v[46:47], v[46:47], 0, s[18:19]
	v_lshl_add_u64 v[48:49], v[48:49], 0, s[14:15]
	v_add_u32_e32 v52, 0x8400, v52
	s_cmp_lg_u32 s20, 0
	v_lshl_add_u64 v[34:35], v[34:35], 0, s[14:15]
	v_lshl_add_u64 v[60:61], s[92:93], 0, v[60:61]
	v_lshlrev_b32_e32 v62, 16, v58
	v_and_b32_e32 v63, 0xffff0000, v58
	v_lshlrev_b32_e32 v58, 16, v59
	v_and_b32_e32 v59, 0xffff0000, v59
	v_pk_mul_f32 v[54:55], v[54:55], v[62:63]
	v_pk_mul_f32 v[56:57], v[56:57], v[58:59]
	v_cvt_pk_bf16_f32 v54, v54, v55
	v_cvt_pk_bf16_f32 v55, v56, v57
	global_store_dwordx2 v[60:61], v[54:55], off
	v_add_u32_e32 v53, v52, v174
	ds_read2_b64 v[54:57], v53 offset1:4
	ds_read2_b64 v[58:61], v53 offset0:8 offset1:12
	s_waitcnt lgkmcnt(1)
	v_mfma_f32_16x16x32_bf16 v[54:57], v[54:57], v[2:5], 0
	s_waitcnt lgkmcnt(0)
	v_mfma_f32_16x16x32_bf16 v[54:57], v[58:61], v[6:9], v[54:57]
	ds_read2_b64 v[58:61], v53 offset0:16 offset1:20
	s_waitcnt lgkmcnt(0)
	v_mfma_f32_16x16x32_bf16 v[54:57], v[58:61], v[10:13], v[54:57]
	ds_read2_b64 v[58:61], v53 offset0:24 offset1:28
	s_waitcnt lgkmcnt(0)
	v_mfma_f32_16x16x32_bf16 v[54:57], v[58:61], v[14:17], v[54:57]
	ds_read2_b64 v[58:61], v53 offset0:32 offset1:36
	s_waitcnt lgkmcnt(0)
	v_mfma_f32_16x16x32_bf16 v[54:57], v[58:61], v[18:21], v[54:57]
	ds_read2_b64 v[58:61], v53 offset0:40 offset1:44
	s_waitcnt lgkmcnt(0)
	v_mfma_f32_16x16x32_bf16 v[54:57], v[58:61], v[22:25], v[54:57]
	ds_read2_b64 v[58:61], v53 offset0:48 offset1:52
	s_waitcnt lgkmcnt(0)
	v_mfma_f32_16x16x32_bf16 v[54:57], v[58:61], v[26:29], v[54:57]
	ds_read2_b64 v[58:61], v53 offset0:56 offset1:60
	s_waitcnt lgkmcnt(0)
	v_mfma_f32_16x16x32_bf16 v[54:57], v[58:61], v[30:33], v[54:57]
	v_lshl_add_u64 v[58:59], s[92:93], 0, v[46:47]
	v_mov_b32_e32 v70, v216
	v_mov_b32_e32 v71, v217
	v_add_u32_e32 v66, 0x2000, v53
	ds_read2_b64 v[58:61], v66 offset0:32 offset1:36
	ds_read2_b64 v[62:65], v66 offset0:40 offset1:44
	v_lshl_add_u64 v[72:73], s[92:93], 0, v[48:49]
	s_waitcnt lgkmcnt(1)
	v_mfma_f32_16x16x32_bf16 v[58:61], v[58:61], v[2:5], 0
	s_waitcnt lgkmcnt(0)
	v_mfma_f32_16x16x32_bf16 v[58:61], v[62:65], v[6:9], v[58:61]
	ds_read2_b64 v[62:65], v66 offset0:48 offset1:52
	s_waitcnt lgkmcnt(0)
	v_mfma_f32_16x16x32_bf16 v[58:61], v[62:65], v[10:13], v[58:61]
	ds_read2_b64 v[62:65], v66 offset0:56 offset1:60
	s_waitcnt lgkmcnt(0)
	v_mfma_f32_16x16x32_bf16 v[58:61], v[62:65], v[14:17], v[58:61]
	ds_read2_b64 v[62:65], v66 offset0:64 offset1:68
	s_waitcnt lgkmcnt(0)
	v_mfma_f32_16x16x32_bf16 v[58:61], v[62:65], v[18:21], v[58:61]
	ds_read2_b64 v[62:65], v66 offset0:72 offset1:76
	s_waitcnt lgkmcnt(0)
	v_mfma_f32_16x16x32_bf16 v[58:61], v[62:65], v[22:25], v[58:61]
	ds_read2_b64 v[62:65], v66 offset0:80 offset1:84
	ds_read2_b64 v[66:69], v66 offset0:88 offset1:92
	s_waitcnt lgkmcnt(1)
	v_mfma_f32_16x16x32_bf16 v[58:61], v[62:65], v[26:29], v[58:61]
	v_lshlrev_b32_e32 v62, 16, v70
	v_and_b32_e32 v63, 0xffff0000, v70
	v_lshlrev_b32_e32 v64, 16, v71
	v_and_b32_e32 v65, 0xffff0000, v71
	v_pk_mul_f32 v[54:55], v[54:55], v[62:63]
	v_pk_mul_f32 v[56:57], v[56:57], v[64:65]
	v_cvt_pk_bf16_f32 v54, v54, v55
	v_cvt_pk_bf16_f32 v55, v56, v57
	global_store_dwordx2 v[72:73], v[54:55], off
	s_waitcnt lgkmcnt(0)
	v_mfma_f32_16x16x32_bf16 v[54:57], v[66:69], v[30:33], v[58:61]
	s_nop 2
	v_lshl_add_u64 v[58:59], s[92:93], 0, v[44:45]
	v_mov_b32_e32 v74, v218
	v_mov_b32_e32 v75, v219
	v_add_u32_e32 v76, 0x4000, v53
	ds_read2_b64 v[58:61], v76 offset0:64 offset1:68
	ds_read2_b64 v[62:65], v76 offset0:72 offset1:76
	ds_read2_b64 v[66:69], v76 offset0:80 offset1:84
	s_waitcnt lgkmcnt(2)
	v_mfma_f32_16x16x32_bf16 v[58:61], v[58:61], v[2:5], 0
	ds_read2_b64 v[70:73], v76 offset0:112 offset1:116
	v_add_u32_e32 v77, s0, v174
	v_subrev_u32_e32 v78, 32, v77
	s_waitcnt lgkmcnt(2)
	v_mfma_f32_16x16x32_bf16 v[58:61], v[62:65], v[6:9], v[58:61]
	ds_read2_b64 v[62:65], v76 offset0:88 offset1:92
	s_waitcnt lgkmcnt(2)
	v_mfma_f32_16x16x32_bf16 v[58:61], v[66:69], v[10:13], v[58:61]
	ds_read2_b64 v[66:69], v76 offset0:96 offset1:100
	s_waitcnt lgkmcnt(1)
	v_mfma_f32_16x16x32_bf16 v[58:61], v[62:65], v[14:17], v[58:61]
	ds_read2_b64 v[62:65], v76 offset0:104 offset1:108
	s_waitcnt lgkmcnt(1)
	v_mfma_f32_16x16x32_bf16 v[58:61], v[66:69], v[18:21], v[58:61]
	ds_read2_b64 v[66:69], v76 offset0:120 offset1:124
	v_and_or_b32 v76, v78, 56, v50
	v_bitop3_b32 v90, v76, s33, v51 bitop3:0xde
	s_waitcnt lgkmcnt(1)
	v_mfma_f32_16x16x32_bf16 v[58:61], v[62:65], v[22:25], v[58:61]
	v_lshl_add_u64 v[62:63], v[42:43], 0, v[90:91]
	v_lshl_add_u64 v[62:63], s[92:93], 0, v[62:63]
	v_lshlrev_b32_e32 v64, 16, v74
	v_mfma_f32_16x16x32_bf16 v[58:61], v[70:73], v[26:29], v[58:61]
	v_and_b32_e32 v65, 0xffff0000, v74
	v_lshlrev_b32_e32 v70, 16, v75
	v_and_b32_e32 v71, 0xffff0000, v75
	v_pk_mul_f32 v[54:55], v[54:55], v[64:65]
	v_pk_mul_f32 v[56:57], v[56:57], v[70:71]
	v_cvt_pk_bf16_f32 v54, v54, v55
	v_cvt_pk_bf16_f32 v55, v56, v57
	global_store_dwordx2 v[62:63], v[54:55], off
	s_waitcnt lgkmcnt(0)
	v_mfma_f32_16x16x32_bf16 v[54:57], v[66:69], v[30:33], v[58:61]
	s_nop 2
	v_lshl_add_u64 v[58:59], s[92:93], 0, v[40:41]
	v_mov_b32_e32 v70, v220
	v_mov_b32_e32 v71, v221
	v_add_u32_e32 v53, 0x6000, v53
	ds_read2_b64 v[58:61], v53 offset0:96 offset1:100
	ds_read2_b64 v[62:65], v53 offset0:104 offset1:108
	ds_read2_b64 v[66:69], v53 offset0:152 offset1:156
	v_lshl_add_u64 v[72:73], s[92:93], 0, v[38:39]
	s_waitcnt lgkmcnt(2)
	v_mfma_f32_16x16x32_bf16 v[58:61], v[58:61], v[2:5], 0
	s_waitcnt lgkmcnt(1)
	v_mfma_f32_16x16x32_bf16 v[58:61], v[62:65], v[6:9], v[58:61]
	ds_read2_b64 v[62:65], v53 offset0:112 offset1:116
	s_waitcnt lgkmcnt(0)
	v_mfma_f32_16x16x32_bf16 v[58:61], v[62:65], v[10:13], v[58:61]
	ds_read2_b64 v[62:65], v53 offset0:120 offset1:124
	s_waitcnt lgkmcnt(0)
	v_mfma_f32_16x16x32_bf16 v[58:61], v[62:65], v[14:17], v[58:61]
	ds_read2_b64 v[62:65], v53 offset0:128 offset1:132
	s_waitcnt lgkmcnt(0)
	v_mfma_f32_16x16x32_bf16 v[58:61], v[62:65], v[18:21], v[58:61]
	ds_read2_b64 v[62:65], v53 offset0:136 offset1:140
	s_waitcnt lgkmcnt(0)
	v_mfma_f32_16x16x32_bf16 v[58:61], v[62:65], v[22:25], v[58:61]
	ds_read2_b64 v[62:65], v53 offset0:144 offset1:148
	s_waitcnt lgkmcnt(0)
	v_mfma_f32_16x16x32_bf16 v[58:61], v[62:65], v[26:29], v[58:61]
	v_lshlrev_b32_e32 v62, 16, v70
	v_and_b32_e32 v63, 0xffff0000, v70
	v_lshlrev_b32_e32 v64, 16, v71
	v_and_b32_e32 v65, 0xffff0000, v71
	v_pk_mul_f32 v[54:55], v[54:55], v[62:63]
	v_pk_mul_f32 v[56:57], v[56:57], v[64:65]
	v_cvt_pk_bf16_f32 v54, v54, v55
	v_cvt_pk_bf16_f32 v55, v56, v57
	global_store_dwordx2 v[72:73], v[54:55], off
	v_mfma_f32_16x16x32_bf16 v[54:57], v[66:69], v[30:33], v[58:61]
	s_nop 2
	v_lshl_add_u64 v[58:59], s[92:93], 0, v[36:37]
	v_mov_b32_e32 v58, v222
	v_mov_b32_e32 v59, v223
	v_add_u32_e32 v53, 32, v77
	v_and_or_b32 v53, v53, 56, v50
	v_xad_u32 v90, v53, v51, s33
	s_addk_i32 s0, 0x80
	s_add_i32 s20, s20, -4
	v_lshl_add_u64 v[60:61], v[34:35], 0, v[90:91]
	v_lshl_add_u64 v[36:37], v[36:37], 0, s[18:19]
	v_lshl_add_u64 v[38:39], v[38:39], 0, s[14:15]
	v_lshl_add_u64 v[40:41], v[40:41], 0, s[18:19]
	v_lshl_add_u64 v[42:43], v[42:43], 0, s[14:15]
	v_lshl_add_u64 v[44:45], v[44:45], 0, s[18:19]
	v_lshl_add_u64 v[46:47], v[46:47], 0, s[18:19]
	v_lshl_add_u64 v[48:49], v[48:49], 0, s[14:15]
	v_add_u32_e32 v52, 0x8400, v52
	s_cmp_lg_u32 s20, 0
	v_lshl_add_u64 v[34:35], v[34:35], 0, s[14:15]
	v_lshl_add_u64 v[60:61], s[92:93], 0, v[60:61]
	v_lshlrev_b32_e32 v62, 16, v58
	v_and_b32_e32 v63, 0xffff0000, v58
	v_lshlrev_b32_e32 v58, 16, v59
	v_and_b32_e32 v59, 0xffff0000, v59
	v_pk_mul_f32 v[54:55], v[54:55], v[62:63]
	v_pk_mul_f32 v[56:57], v[56:57], v[58:59]
	v_cvt_pk_bf16_f32 v54, v54, v55
	v_cvt_pk_bf16_f32 v55, v56, v57
	global_store_dwordx2 v[60:61], v[54:55], off
	v_add_u32_e32 v53, v52, v174
	ds_read2_b64 v[54:57], v53 offset1:4
	ds_read2_b64 v[58:61], v53 offset0:8 offset1:12
	s_waitcnt lgkmcnt(1)
	v_mfma_f32_16x16x32_bf16 v[54:57], v[54:57], v[2:5], 0
	s_waitcnt lgkmcnt(0)
	v_mfma_f32_16x16x32_bf16 v[54:57], v[58:61], v[6:9], v[54:57]
	ds_read2_b64 v[58:61], v53 offset0:16 offset1:20
	s_waitcnt lgkmcnt(0)
	v_mfma_f32_16x16x32_bf16 v[54:57], v[58:61], v[10:13], v[54:57]
	ds_read2_b64 v[58:61], v53 offset0:24 offset1:28
	s_waitcnt lgkmcnt(0)
	v_mfma_f32_16x16x32_bf16 v[54:57], v[58:61], v[14:17], v[54:57]
	ds_read2_b64 v[58:61], v53 offset0:32 offset1:36
	s_waitcnt lgkmcnt(0)
	v_mfma_f32_16x16x32_bf16 v[54:57], v[58:61], v[18:21], v[54:57]
	ds_read2_b64 v[58:61], v53 offset0:40 offset1:44
	s_waitcnt lgkmcnt(0)
	v_mfma_f32_16x16x32_bf16 v[54:57], v[58:61], v[22:25], v[54:57]
	ds_read2_b64 v[58:61], v53 offset0:48 offset1:52
	s_waitcnt lgkmcnt(0)
	v_mfma_f32_16x16x32_bf16 v[54:57], v[58:61], v[26:29], v[54:57]
	ds_read2_b64 v[58:61], v53 offset0:56 offset1:60
	s_waitcnt lgkmcnt(0)
	v_mfma_f32_16x16x32_bf16 v[54:57], v[58:61], v[30:33], v[54:57]
	v_lshl_add_u64 v[58:59], s[92:93], 0, v[46:47]
	v_mov_b32_e32 v70, v224
	v_mov_b32_e32 v71, v225
	v_add_u32_e32 v66, 0x2000, v53
	ds_read2_b64 v[58:61], v66 offset0:32 offset1:36
	ds_read2_b64 v[62:65], v66 offset0:40 offset1:44
	v_lshl_add_u64 v[72:73], s[92:93], 0, v[48:49]
	s_waitcnt lgkmcnt(1)
	v_mfma_f32_16x16x32_bf16 v[58:61], v[58:61], v[2:5], 0
	s_waitcnt lgkmcnt(0)
	v_mfma_f32_16x16x32_bf16 v[58:61], v[62:65], v[6:9], v[58:61]
	ds_read2_b64 v[62:65], v66 offset0:48 offset1:52
	s_waitcnt lgkmcnt(0)
	v_mfma_f32_16x16x32_bf16 v[58:61], v[62:65], v[10:13], v[58:61]
	ds_read2_b64 v[62:65], v66 offset0:56 offset1:60
	s_waitcnt lgkmcnt(0)
	v_mfma_f32_16x16x32_bf16 v[58:61], v[62:65], v[14:17], v[58:61]
	ds_read2_b64 v[62:65], v66 offset0:64 offset1:68
	s_waitcnt lgkmcnt(0)
	v_mfma_f32_16x16x32_bf16 v[58:61], v[62:65], v[18:21], v[58:61]
	ds_read2_b64 v[62:65], v66 offset0:72 offset1:76
	s_waitcnt lgkmcnt(0)
	v_mfma_f32_16x16x32_bf16 v[58:61], v[62:65], v[22:25], v[58:61]
	ds_read2_b64 v[62:65], v66 offset0:80 offset1:84
	ds_read2_b64 v[66:69], v66 offset0:88 offset1:92
	s_waitcnt lgkmcnt(1)
	v_mfma_f32_16x16x32_bf16 v[58:61], v[62:65], v[26:29], v[58:61]
	v_lshlrev_b32_e32 v62, 16, v70
	v_and_b32_e32 v63, 0xffff0000, v70
	v_lshlrev_b32_e32 v64, 16, v71
	v_and_b32_e32 v65, 0xffff0000, v71
	v_pk_mul_f32 v[54:55], v[54:55], v[62:63]
	v_pk_mul_f32 v[56:57], v[56:57], v[64:65]
	v_cvt_pk_bf16_f32 v54, v54, v55
	v_cvt_pk_bf16_f32 v55, v56, v57
	global_store_dwordx2 v[72:73], v[54:55], off
	s_waitcnt lgkmcnt(0)
	v_mfma_f32_16x16x32_bf16 v[54:57], v[66:69], v[30:33], v[58:61]
	s_nop 2
	v_lshl_add_u64 v[58:59], s[92:93], 0, v[44:45]
	v_mov_b32_e32 v74, v226
	v_mov_b32_e32 v75, v227
	v_add_u32_e32 v76, 0x4000, v53
	ds_read2_b64 v[58:61], v76 offset0:64 offset1:68
	ds_read2_b64 v[62:65], v76 offset0:72 offset1:76
	ds_read2_b64 v[66:69], v76 offset0:80 offset1:84
	s_waitcnt lgkmcnt(2)
	v_mfma_f32_16x16x32_bf16 v[58:61], v[58:61], v[2:5], 0
	ds_read2_b64 v[70:73], v76 offset0:112 offset1:116
	v_add_u32_e32 v77, s0, v174
	v_subrev_u32_e32 v78, 32, v77
	s_waitcnt lgkmcnt(2)
	v_mfma_f32_16x16x32_bf16 v[58:61], v[62:65], v[6:9], v[58:61]
	ds_read2_b64 v[62:65], v76 offset0:88 offset1:92
	s_waitcnt lgkmcnt(2)
	v_mfma_f32_16x16x32_bf16 v[58:61], v[66:69], v[10:13], v[58:61]
	ds_read2_b64 v[66:69], v76 offset0:96 offset1:100
	s_waitcnt lgkmcnt(1)
	v_mfma_f32_16x16x32_bf16 v[58:61], v[62:65], v[14:17], v[58:61]
	ds_read2_b64 v[62:65], v76 offset0:104 offset1:108
	s_waitcnt lgkmcnt(1)
	v_mfma_f32_16x16x32_bf16 v[58:61], v[66:69], v[18:21], v[58:61]
	ds_read2_b64 v[66:69], v76 offset0:120 offset1:124
	v_and_or_b32 v76, v78, 56, v50
	v_bitop3_b32 v90, v76, s33, v51 bitop3:0xde
	s_waitcnt lgkmcnt(1)
	v_mfma_f32_16x16x32_bf16 v[58:61], v[62:65], v[22:25], v[58:61]
	v_lshl_add_u64 v[62:63], v[42:43], 0, v[90:91]
	v_lshl_add_u64 v[62:63], s[92:93], 0, v[62:63]
	v_lshlrev_b32_e32 v64, 16, v74
	v_mfma_f32_16x16x32_bf16 v[58:61], v[70:73], v[26:29], v[58:61]
	v_and_b32_e32 v65, 0xffff0000, v74
	v_lshlrev_b32_e32 v70, 16, v75
	v_and_b32_e32 v71, 0xffff0000, v75
	v_pk_mul_f32 v[54:55], v[54:55], v[64:65]
	v_pk_mul_f32 v[56:57], v[56:57], v[70:71]
	v_cvt_pk_bf16_f32 v54, v54, v55
	v_cvt_pk_bf16_f32 v55, v56, v57
	global_store_dwordx2 v[62:63], v[54:55], off
	s_waitcnt lgkmcnt(0)
	v_mfma_f32_16x16x32_bf16 v[54:57], v[66:69], v[30:33], v[58:61]
	s_nop 2
	v_lshl_add_u64 v[58:59], s[92:93], 0, v[40:41]
	v_mov_b32_e32 v70, v228
	v_mov_b32_e32 v71, v229
	v_add_u32_e32 v53, 0x6000, v53
	ds_read2_b64 v[58:61], v53 offset0:96 offset1:100
	ds_read2_b64 v[62:65], v53 offset0:104 offset1:108
	ds_read2_b64 v[66:69], v53 offset0:152 offset1:156
	v_lshl_add_u64 v[72:73], s[92:93], 0, v[38:39]
	s_waitcnt lgkmcnt(2)
	v_mfma_f32_16x16x32_bf16 v[58:61], v[58:61], v[2:5], 0
	s_waitcnt lgkmcnt(1)
	v_mfma_f32_16x16x32_bf16 v[58:61], v[62:65], v[6:9], v[58:61]
	ds_read2_b64 v[62:65], v53 offset0:112 offset1:116
	s_waitcnt lgkmcnt(0)
	v_mfma_f32_16x16x32_bf16 v[58:61], v[62:65], v[10:13], v[58:61]
	ds_read2_b64 v[62:65], v53 offset0:120 offset1:124
	s_waitcnt lgkmcnt(0)
	v_mfma_f32_16x16x32_bf16 v[58:61], v[62:65], v[14:17], v[58:61]
	ds_read2_b64 v[62:65], v53 offset0:128 offset1:132
	s_waitcnt lgkmcnt(0)
	v_mfma_f32_16x16x32_bf16 v[58:61], v[62:65], v[18:21], v[58:61]
	ds_read2_b64 v[62:65], v53 offset0:136 offset1:140
	s_waitcnt lgkmcnt(0)
	v_mfma_f32_16x16x32_bf16 v[58:61], v[62:65], v[22:25], v[58:61]
	ds_read2_b64 v[62:65], v53 offset0:144 offset1:148
	s_waitcnt lgkmcnt(0)
	v_mfma_f32_16x16x32_bf16 v[58:61], v[62:65], v[26:29], v[58:61]
	v_lshlrev_b32_e32 v62, 16, v70
	v_and_b32_e32 v63, 0xffff0000, v70
	v_lshlrev_b32_e32 v64, 16, v71
	v_and_b32_e32 v65, 0xffff0000, v71
	v_pk_mul_f32 v[54:55], v[54:55], v[62:63]
	v_pk_mul_f32 v[56:57], v[56:57], v[64:65]
	v_cvt_pk_bf16_f32 v54, v54, v55
	v_cvt_pk_bf16_f32 v55, v56, v57
	global_store_dwordx2 v[72:73], v[54:55], off
	v_mfma_f32_16x16x32_bf16 v[54:57], v[66:69], v[30:33], v[58:61]
	s_nop 2
	v_lshl_add_u64 v[58:59], s[92:93], 0, v[36:37]
	v_mov_b32_e32 v58, v230
	v_mov_b32_e32 v59, v231
	v_add_u32_e32 v53, 32, v77
	v_and_or_b32 v53, v53, 56, v50
	v_xad_u32 v90, v53, v51, s33
	s_addk_i32 s0, 0x80
	s_add_i32 s20, s20, -4
	v_lshl_add_u64 v[60:61], v[34:35], 0, v[90:91]
	v_lshl_add_u64 v[36:37], v[36:37], 0, s[18:19]
	v_lshl_add_u64 v[38:39], v[38:39], 0, s[14:15]
	v_lshl_add_u64 v[40:41], v[40:41], 0, s[18:19]
	v_lshl_add_u64 v[42:43], v[42:43], 0, s[14:15]
	v_lshl_add_u64 v[44:45], v[44:45], 0, s[18:19]
	v_lshl_add_u64 v[46:47], v[46:47], 0, s[18:19]
	v_lshl_add_u64 v[48:49], v[48:49], 0, s[14:15]
	v_add_u32_e32 v52, 0x8400, v52
	s_cmp_lg_u32 s20, 0
	v_lshl_add_u64 v[34:35], v[34:35], 0, s[14:15]
	v_lshl_add_u64 v[60:61], s[92:93], 0, v[60:61]
	v_lshlrev_b32_e32 v62, 16, v58
	v_and_b32_e32 v63, 0xffff0000, v58
	v_lshlrev_b32_e32 v58, 16, v59
	v_and_b32_e32 v59, 0xffff0000, v59
	v_pk_mul_f32 v[54:55], v[54:55], v[62:63]
	v_pk_mul_f32 v[56:57], v[56:57], v[58:59]
	v_cvt_pk_bf16_f32 v54, v54, v55
	v_cvt_pk_bf16_f32 v55, v56, v57
	global_store_dwordx2 v[60:61], v[54:55], off
	v_readlane_b32 s20, v249, 34
	s_add_i32 s42, s42, s20
	s_add_i32 s36, s36, s37
	s_cmpk_gt_i32 s42, 0xff
	v_readlane_b32 s21, v249, 35
	s_cbranch_scc0 .LBB0_655

.LBB0_1451:
	v_lshl_add_u64 v[82:83], v[76:77], 0, v[68:69]
	v_lshl_add_u64 v[86:87], v[74:75], 0, v[68:69]
	v_lshl_add_u64 v[192:193], v[72:73], 0, v[68:69]
	v_lshl_add_u64 v[196:197], v[70:71], 0, v[68:69]
	global_load_dwordx4 v[82:85], v[82:83], off
	s_nop 0
	global_load_dwordx4 v[86:89], v[86:87], off
	s_nop 0
	global_load_dwordx4 v[192:195], v[192:193], off
	s_nop 0
	global_load_dwordx4 v[196:199], v[196:197], off
	v_add_u32_e32 v67, 0x800, v67
	v_cmp_lt_u32_e32 vcc, s38, v67
	v_add_u32_e32 v90, v80, v66
	v_add_u32_e32 v103, v81, v66
	v_add_u32_e32 v191, v79, v66
	v_add_u32_e32 v200, v78, v66
	v_add_u32_e32 v78, 0x8400, v78
	v_lshl_add_u64 v[70:71], v[70:71], 0, s[10:11]
	v_add_u32_e32 v79, 0x8400, v79
	v_lshl_add_u64 v[72:73], v[72:73], 0, s[10:11]
	v_lshl_add_u64 v[76:77], v[76:77], 0, s[10:11]
	v_add_u32_e32 v80, 0x8400, v80
	v_add_u32_e32 v81, 0x8400, v81
	v_lshl_add_u64 v[74:75], v[74:75], 0, s[10:11]
	s_or_b64 s[20:21], vcc, s[20:21]
	s_waitcnt vmcnt(3)
	ds_write_b128 v90, v[82:85]
	s_waitcnt vmcnt(2)
	ds_write_b128 v103, v[86:89]
	s_waitcnt vmcnt(1)
	ds_write_b128 v191, v[192:195]
	s_waitcnt vmcnt(0)
	ds_write_b128 v200, v[196:199]
	s_andn2_b64 exec, exec, s[20:21]
	s_cbranch_execnz .LBB0_1451
	s_or_b64 exec, exec, s[20:21]
	v_mul_f32_e32 v68, 0x3d800000, v6
	v_mul_f32_e32 v69, 0x3d800000, v7
	v_max3_f32 v68, v68, s41, v69
	v_mul_f32_e32 v69, 0x3d800000, v8
	v_mul_f32_e32 v70, 0x3d800000, v9
	v_max3_f32 v68, v68, v69, v70
	v_mul_f32_e32 v69, 0x3d800000, v2
	v_mul_f32_e32 v70, 0x3d800000, v3
	v_max3_f32 v68, v68, v69, v70
	v_mul_f32_e32 v69, 0x3d800000, v4
	v_mul_f32_e32 v70, 0x3d800000, v5
	v_max3_f32 v68, v68, v69, v70
	v_mul_f32_e32 v69, 0x3d800000, v10
	v_mul_f32_e32 v70, 0x3d800000, v11
	v_max3_f32 v68, v68, v69, v70
	v_mul_f32_e32 v69, 0x3d800000, v12
	v_mul_f32_e32 v70, 0x3d800000, v13
	v_max3_f32 v68, v68, v69, v70
	v_mul_f32_e32 v69, 0x3d800000, v14
	v_mul_f32_e32 v70, 0x3d800000, v15
	v_max3_f32 v68, v68, v69, v70
	v_mul_f32_e32 v69, 0x3d800000, v16
	v_mul_f32_e32 v70, 0x3d800000, v17
	v_max3_f32 v68, v68, v69, v70
	v_mul_f32_e32 v69, 0x3d800000, v18
	v_mul_f32_e32 v70, 0x3d800000, v19
	v_max3_f32 v68, v68, v69, v70
	v_mul_f32_e32 v69, 0x3d800000, v20
	v_mul_f32_e32 v70, 0x3d800000, v21
	v_max3_f32 v68, v68, v69, v70
	v_mul_f32_e32 v69, 0x3d800000, v22
	v_mul_f32_e32 v70, 0x3d800000, v23
	v_max3_f32 v68, v68, v69, v70
	v_mul_f32_e32 v69, 0x3d800000, v24
	v_mul_f32_e32 v70, 0x3d800000, v25
	v_max3_f32 v68, v68, v69, v70
	v_mul_f32_e32 v69, 0x3d800000, v26
	v_mul_f32_e32 v70, 0x3d800000, v27
	v_max3_f32 v68, v68, v69, v70
	v_mul_f32_e32 v69, 0x3d800000, v28
	v_mul_f32_e32 v70, 0x3d800000, v29
	v_max3_f32 v68, v68, v69, v70
	v_mul_f32_e32 v69, 0x3d800000, v30
	v_mul_f32_e32 v70, 0x3d800000, v31
	v_max3_f32 v68, v68, v69, v70
	v_mul_f32_e32 v69, 0x3d800000, v32
	v_mul_f32_e32 v70, 0x3d800000, v33
	v_max3_f32 v68, v68, v69, v70
	v_mul_f32_e32 v69, 0x3d800000, v34
	v_mul_f32_e32 v70, 0x3d800000, v35
	v_max3_f32 v68, v68, v69, v70
	v_mul_f32_e32 v69, 0x3d800000, v36
	v_mul_f32_e32 v70, 0x3d800000, v37
	v_max3_f32 v68, v68, v69, v70
	v_mul_f32_e32 v69, 0x3d800000, v38
	v_mul_f32_e32 v70, 0x3d800000, v39
	v_max3_f32 v68, v68, v69, v70
	v_mul_f32_e32 v69, 0x3d800000, v40
	v_mul_f32_e32 v70, 0x3d800000, v41
	v_max3_f32 v68, v68, v69, v70
	v_mul_f32_e32 v69, 0x3d800000, v42
	v_mul_f32_e32 v70, 0x3d800000, v43
	v_max3_f32 v68, v68, v69, v70
	v_mul_f32_e32 v69, 0x3d800000, v44
	v_mul_f32_e32 v70, 0x3d800000, v45
	v_max3_f32 v68, v68, v69, v70
	v_mul_f32_e32 v69, 0x3d800000, v46
	v_mul_f32_e32 v70, 0x3d800000, v47
	v_max3_f32 v68, v68, v69, v70
	v_mul_f32_e32 v69, 0x3d800000, v48
	v_mul_f32_e32 v70, 0x3d800000, v49
	v_max3_f32 v68, v68, v69, v70
	v_mul_f32_e32 v69, 0x3d800000, v50
	v_mul_f32_e32 v70, 0x3d800000, v51
	v_max3_f32 v68, v68, v69, v70
	v_mul_f32_e32 v69, 0x3d800000, v52
	v_mul_f32_e32 v70, 0x3d800000, v53
	v_max3_f32 v68, v68, v69, v70
	v_mul_f32_e32 v69, 0x3d800000, v54
	v_mul_f32_e32 v70, 0x3d800000, v55
	v_max3_f32 v68, v68, v69, v70
	v_mul_f32_e32 v69, 0x3d800000, v56
	v_mul_f32_e32 v70, 0x3d800000, v57
	v_max3_f32 v68, v68, v69, v70
	v_mul_f32_e32 v69, 0x3d800000, v58
	v_mul_f32_e32 v70, 0x3d800000, v59
	v_max3_f32 v68, v68, v69, v70
	v_mul_f32_e32 v69, 0x3d800000, v60
	v_mul_f32_e32 v70, 0x3d800000, v61
	v_max3_f32 v68, v68, v69, v70
	v_mul_f32_e32 v69, 0x3d800000, v62
	v_mul_f32_e32 v70, 0x3d800000, v63
	v_max3_f32 v68, v68, v69, v70
	v_mul_f32_e32 v69, 0x3d800000, v64
	v_mul_f32_e32 v70, 0x3d800000, v65
	v_max3_f32 v68, v68, v69, v70
	v_and_b32_e32 v70, 64, v189
	v_xor_b32_e32 v69, 16, v189
	v_add_u32_e32 v70, 64, v70
	v_cmp_lt_i32_e32 vcc, v69, v70
	s_lshl_b32 s20, s45, 8
	v_or_b32_e32 v74, s20, v183
	v_cndmask_b32_e32 v69, v189, v69, vcc
	v_lshlrev_b32_e32 v69, 2, v69
	ds_bpermute_b32 v71, v69, v68
	s_or_b32 s0, s46, 64
	s_and_b32 s21, s36, 0xf80
	v_add_lshl_u32 v72, v182, s20, 8
	v_add_lshl_u32 v66, v177, s20, 8
	s_waitcnt lgkmcnt(0)
	v_max_f32_e32 v71, v71, v71
	v_max_f32_e32 v75, v68, v71
	v_xor_b32_e32 v68, 32, v189
	v_cmp_lt_i32_e32 vcc, v68, v70
	v_lshlrev_b32_e32 v70, 1, v74
	v_and_b32_e32 v72, 0x1fc000, v72
	v_cndmask_b32_e32 v68, v189, v68, vcc
	v_lshlrev_b32_e32 v80, 2, v68
	ds_bpermute_b32 v76, v80, v75
	v_mov_b32_e32 v73, v91
	v_and_b32_e32 v90, 0x1fc000, v66
	v_or_b32_e32 v66, s20, v181
	v_add_lshl_u32 v68, v185, s20, 8
	s_waitcnt lgkmcnt(0)
	v_max_f32_e32 v74, v76, v76
	v_max_f32_e32 v78, v75, v74
	v_fma_f32 v2, v2, s40, -v78
	v_mul_f32_e32 v2, 0x3fb8aa3b, v2
	v_exp_f32_e32 v74, v2
	v_fma_f32 v2, v3, s40, -v78
	v_mul_f32_e32 v2, 0x3fb8aa3b, v2
	v_exp_f32_e32 v75, v2
	v_fma_f32 v2, v4, s40, -v78
	v_mul_f32_e32 v2, 0x3fb8aa3b, v2
	v_exp_f32_e32 v76, v2
	v_fma_f32 v2, v5, s40, -v78
	v_mul_f32_e32 v2, 0x3fb8aa3b, v2
	v_exp_f32_e32 v77, v2
	v_fma_f32 v2, v10, s40, -v78
	v_mul_f32_e32 v2, 0x3fb8aa3b, v2
	v_exp_f32_e32 v10, v2
	v_fma_f32 v2, v11, s40, -v78
	v_mul_f32_e32 v2, 0x3fb8aa3b, v2
	v_exp_f32_e32 v11, v2
	v_fma_f32 v2, v12, s40, -v78
	v_mul_f32_e32 v2, 0x3fb8aa3b, v2
	v_exp_f32_e32 v12, v2
	v_fma_f32 v2, v13, s40, -v78
	v_mul_f32_e32 v2, 0x3fb8aa3b, v2
	v_exp_f32_e32 v13, v2
	v_fma_f32 v2, v14, s40, -v78
	v_mul_f32_e32 v2, 0x3fb8aa3b, v2
	v_exp_f32_e32 v14, v2
	v_fma_f32 v2, v15, s40, -v78
	v_mul_f32_e32 v2, 0x3fb8aa3b, v2
	v_exp_f32_e32 v15, v2
	v_fma_f32 v2, v16, s40, -v78
	v_mul_f32_e32 v2, 0x3fb8aa3b, v2
	v_exp_f32_e32 v16, v2
	v_fma_f32 v2, v17, s40, -v78
	v_mul_f32_e32 v2, 0x3fb8aa3b, v2
	v_exp_f32_e32 v17, v2
	v_fma_f32 v2, v18, s40, -v78
	v_mul_f32_e32 v2, 0x3fb8aa3b, v2
	v_exp_f32_e32 v18, v2
	v_fma_f32 v2, v19, s40, -v78
	v_mul_f32_e32 v2, 0x3fb8aa3b, v2
	v_exp_f32_e32 v19, v2
	v_fma_f32 v2, v20, s40, -v78
	v_mul_f32_e32 v2, 0x3fb8aa3b, v2
	v_exp_f32_e32 v20, v2
	v_fma_f32 v2, v21, s40, -v78
	v_mul_f32_e32 v2, 0x3fb8aa3b, v2
	v_exp_f32_e32 v21, v2
	v_fma_f32 v2, v22, s40, -v78
	v_mul_f32_e32 v2, 0x3fb8aa3b, v2
	v_exp_f32_e32 v22, v2
	v_fma_f32 v2, v23, s40, -v78
	v_mul_f32_e32 v2, 0x3fb8aa3b, v2
	v_exp_f32_e32 v23, v2
	v_fma_f32 v2, v24, s40, -v78
	v_mul_f32_e32 v2, 0x3fb8aa3b, v2
	v_exp_f32_e32 v24, v2
	v_fma_f32 v2, v25, s40, -v78
	v_mul_f32_e32 v2, 0x3fb8aa3b, v2
	v_exp_f32_e32 v25, v2
	v_fma_f32 v2, v26, s40, -v78
	v_mul_f32_e32 v2, 0x3fb8aa3b, v2
	v_exp_f32_e32 v26, v2
	v_fma_f32 v2, v27, s40, -v78
	v_mul_f32_e32 v2, 0x3fb8aa3b, v2
	v_exp_f32_e32 v27, v2
	v_fma_f32 v2, v28, s40, -v78
	v_mul_f32_e32 v2, 0x3fb8aa3b, v2
	v_exp_f32_e32 v28, v2
	v_fma_f32 v2, v29, s40, -v78
	v_mul_f32_e32 v2, 0x3fb8aa3b, v2
	v_exp_f32_e32 v29, v2
	v_fma_f32 v2, v30, s40, -v78
	v_mul_f32_e32 v2, 0x3fb8aa3b, v2
	v_exp_f32_e32 v30, v2
	v_fma_f32 v2, v31, s40, -v78
	v_mul_f32_e32 v2, 0x3fb8aa3b, v2
	v_exp_f32_e32 v31, v2
	v_fma_f32 v2, v32, s40, -v78
	v_mul_f32_e32 v2, 0x3fb8aa3b, v2
	v_exp_f32_e32 v32, v2
	v_fma_f32 v2, v33, s40, -v78
	v_mul_f32_e32 v2, 0x3fb8aa3b, v2
	v_exp_f32_e32 v33, v2
	v_fma_f32 v2, v34, s40, -v78
	v_mul_f32_e32 v2, 0x3fb8aa3b, v2
	v_exp_f32_e32 v34, v2
	v_fma_f32 v2, v35, s40, -v78
	v_mul_f32_e32 v2, 0x3fb8aa3b, v2
	v_exp_f32_e32 v35, v2
	v_fma_f32 v2, v36, s40, -v78
	v_mul_f32_e32 v2, 0x3fb8aa3b, v2
	v_exp_f32_e32 v36, v2
	v_fma_f32 v2, v37, s40, -v78
	v_mul_f32_e32 v2, 0x3fb8aa3b, v2
	v_exp_f32_e32 v37, v2
	v_fma_f32 v2, v38, s40, -v78
	v_mul_f32_e32 v2, 0x3fb8aa3b, v2
	v_exp_f32_e32 v38, v2
	v_fma_f32 v2, v39, s40, -v78
	v_mul_f32_e32 v2, 0x3fb8aa3b, v2
	v_exp_f32_e32 v39, v2
	v_fma_f32 v2, v40, s40, -v78
	v_mul_f32_e32 v2, 0x3fb8aa3b, v2
	v_exp_f32_e32 v40, v2
	v_fma_f32 v2, v41, s40, -v78
	v_mul_f32_e32 v2, 0x3fb8aa3b, v2
	v_exp_f32_e32 v41, v2
	v_fma_f32 v2, v42, s40, -v78
	v_mul_f32_e32 v2, 0x3fb8aa3b, v2
	v_exp_f32_e32 v42, v2
	v_fma_f32 v2, v43, s40, -v78
	v_mul_f32_e32 v2, 0x3fb8aa3b, v2
	v_exp_f32_e32 v43, v2
	v_fma_f32 v2, v44, s40, -v78
	v_mul_f32_e32 v2, 0x3fb8aa3b, v2
	v_exp_f32_e32 v44, v2
	v_fma_f32 v2, v45, s40, -v78
	v_mul_f32_e32 v2, 0x3fb8aa3b, v2
	v_exp_f32_e32 v45, v2
	v_fma_f32 v2, v46, s40, -v78
	v_mul_f32_e32 v2, 0x3fb8aa3b, v2
	v_exp_f32_e32 v46, v2
	v_fma_f32 v2, v47, s40, -v78
	v_mul_f32_e32 v2, 0x3fb8aa3b, v2
	v_exp_f32_e32 v47, v2
	v_fma_f32 v2, v48, s40, -v78
	v_mul_f32_e32 v2, 0x3fb8aa3b, v2
	v_exp_f32_e32 v48, v2
	v_fma_f32 v2, v49, s40, -v78
	v_mul_f32_e32 v2, 0x3fb8aa3b, v2
	v_exp_f32_e32 v49, v2
	v_fma_f32 v2, v50, s40, -v78
	v_mul_f32_e32 v2, 0x3fb8aa3b, v2
	v_exp_f32_e32 v50, v2
	v_fma_f32 v2, v51, s40, -v78
	v_mul_f32_e32 v2, 0x3fb8aa3b, v2
	v_exp_f32_e32 v51, v2
	v_fma_f32 v2, v52, s40, -v78
	v_mul_f32_e32 v2, 0x3fb8aa3b, v2
	v_exp_f32_e32 v52, v2
	v_fma_f32 v2, v53, s40, -v78
	v_mul_f32_e32 v2, 0x3fb8aa3b, v2
	v_exp_f32_e32 v53, v2
	v_fma_f32 v2, v54, s40, -v78
	v_mul_f32_e32 v2, 0x3fb8aa3b, v2
	v_exp_f32_e32 v54, v2
	v_fma_f32 v2, v55, s40, -v78
	v_mul_f32_e32 v2, 0x3fb8aa3b, v2
	v_exp_f32_e32 v55, v2
	v_fma_f32 v2, v56, s40, -v78
	v_mul_f32_e32 v2, 0x3fb8aa3b, v2
	v_exp_f32_e32 v56, v2
	v_fma_f32 v2, v57, s40, -v78
	v_mul_f32_e32 v2, 0x3fb8aa3b, v2
	v_exp_f32_e32 v57, v2
	v_fma_f32 v2, v58, s40, -v78
	v_mul_f32_e32 v2, 0x3fb8aa3b, v2
	v_exp_f32_e32 v58, v2
	v_fma_f32 v2, v59, s40, -v78
	v_mul_f32_e32 v2, 0x3fb8aa3b, v2
	v_exp_f32_e32 v59, v2
	v_fma_f32 v2, v60, s40, -v78
	v_mul_f32_e32 v2, 0x3fb8aa3b, v2
	v_exp_f32_e32 v60, v2
	v_fma_f32 v2, v61, s40, -v78
	v_mul_f32_e32 v2, 0x3fb8aa3b, v2
	v_exp_f32_e32 v61, v2
	v_fma_f32 v2, v62, s40, -v78
	v_mul_f32_e32 v2, 0x3fb8aa3b, v2
	v_fma_f32 v6, v6, s40, -v78
	v_exp_f32_e32 v62, v2
	v_fma_f32 v2, v63, s40, -v78
	v_mul_f32_e32 v6, 0x3fb8aa3b, v6
	v_fma_f32 v7, v7, s40, -v78
	v_mul_f32_e32 v2, 0x3fb8aa3b, v2
	v_exp_f32_e32 v6, v6
	v_mul_f32_e32 v7, 0x3fb8aa3b, v7
	v_fma_f32 v8, v8, s40, -v78
	v_exp_f32_e32 v63, v2
	v_fma_f32 v2, v64, s40, -v78
	v_exp_f32_e32 v7, v7
	v_mul_f32_e32 v8, 0x3fb8aa3b, v8
	v_fma_f32 v9, v9, s40, -v78
	v_mul_f32_e32 v2, 0x3fb8aa3b, v2
	v_exp_f32_e32 v8, v8
	v_mul_f32_e32 v9, 0x3fb8aa3b, v9
	v_exp_f32_e32 v64, v2
	v_fma_f32 v2, v65, s40, -v78
	v_exp_f32_e32 v9, v9
	v_mul_f32_e32 v2, 0x3fb8aa3b, v2
	v_exp_f32_e32 v65, v2
	v_add_f32_e32 v2, 0, v6
	v_add_f32_e32 v2, v7, v2
	v_add_f32_e32 v2, v8, v2
	v_add_f32_e32 v2, v9, v2
	v_add_f32_e32 v2, v74, v2
	v_add_f32_e32 v2, v75, v2
	v_add_f32_e32 v2, v76, v2
	v_add_f32_e32 v2, v77, v2
	v_add_f32_e32 v2, v10, v2
	v_add_f32_e32 v2, v11, v2
	v_add_f32_e32 v2, v12, v2
	v_add_f32_e32 v2, v13, v2
	v_add_f32_e32 v2, v14, v2
	v_add_f32_e32 v2, v15, v2
	v_add_f32_e32 v2, v16, v2
	v_add_f32_e32 v2, v17, v2
	v_add_f32_e32 v2, v18, v2
	v_add_f32_e32 v2, v19, v2
	v_add_f32_e32 v2, v20, v2
	v_add_f32_e32 v2, v21, v2
	v_add_f32_e32 v2, v22, v2
	v_add_f32_e32 v2, v23, v2
	v_add_f32_e32 v2, v24, v2
	v_add_f32_e32 v2, v25, v2
	v_add_f32_e32 v2, v26, v2
	v_add_f32_e32 v2, v27, v2
	v_add_f32_e32 v2, v28, v2
	v_add_f32_e32 v2, v29, v2
	v_add_f32_e32 v2, v30, v2
	v_add_f32_e32 v2, v31, v2
	v_add_f32_e32 v2, v32, v2
	v_add_f32_e32 v2, v33, v2
	v_add_f32_e32 v2, v34, v2
	v_add_f32_e32 v2, v35, v2
	v_add_f32_e32 v2, v36, v2
	v_add_f32_e32 v2, v37, v2
	v_add_f32_e32 v2, v38, v2
	v_add_f32_e32 v2, v39, v2
	v_add_f32_e32 v2, v40, v2
	v_add_f32_e32 v2, v41, v2
	v_add_f32_e32 v2, v42, v2
	v_add_f32_e32 v2, v43, v2
	v_add_f32_e32 v2, v44, v2
	v_add_f32_e32 v2, v45, v2
	v_add_f32_e32 v2, v46, v2
	v_add_f32_e32 v2, v47, v2
	v_add_f32_e32 v2, v48, v2
	v_add_f32_e32 v2, v49, v2
	v_add_f32_e32 v2, v50, v2
	v_add_f32_e32 v2, v51, v2
	v_add_f32_e32 v2, v52, v2
	v_add_f32_e32 v2, v53, v2
	v_add_f32_e32 v2, v54, v2
	v_add_f32_e32 v2, v55, v2
	v_add_f32_e32 v2, v56, v2
	v_add_f32_e32 v2, v57, v2
	v_add_f32_e32 v2, v58, v2
	v_add_f32_e32 v2, v59, v2
	v_add_f32_e32 v2, v60, v2
	v_add_f32_e32 v2, v61, v2
	v_add_f32_e32 v2, v62, v2
	v_add_f32_e32 v2, v63, v2
	v_add_f32_e32 v2, v64, v2
	v_add_f32_e32 v2, v65, v2
	ds_bpermute_b32 v3, v69, v2
	v_or_b32_e32 v4, s20, v186
	v_lshlrev_b32_e32 v78, 1, v4
	v_or_b32_e32 v4, s20, v173
	v_mov_b32_e32 v83, v91
	s_waitcnt lgkmcnt(0)
	v_add_f32_e32 v2, v2, v3
	ds_bpermute_b32 v3, v80, v2
	v_lshlrev_b32_e32 v80, 1, v4
	v_add_lshl_u32 v4, v187, s20, 8
	v_and_b32_e32 v82, 0x1fc000, v4
	v_lshlrev_b32_e32 v66, 1, v66
	s_waitcnt lgkmcnt(0)
	v_add_f32_e32 v2, v2, v3
	v_div_scale_f32 v3, s[22:23], v2, v2, 1.0
	v_rcp_f32_e32 v5, v3
	s_ashr_i32 s22, s44, 7
	s_ashr_i32 s23, s22, 31
	s_lshl_b64 s[22:23], s[22:23], 20
	v_fma_f32 v4, -v3, v5, 1.0
	v_fmac_f32_e32 v5, v4, v5
	v_div_scale_f32 v4, vcc, 1.0, v2, 1.0
	v_mul_f32_e32 v84, v4, v5
	v_fma_f32 v85, -v3, v84, v4
	v_fmac_f32_e32 v84, v85, v5
	v_fma_f32 v3, -v3, v84, v4
	v_div_fmas_f32 v3, v3, v5, v84
	v_div_fixup_f32 v84, v3, v2, 1.0
	v_pk_mul_f32 v[2:3], v[6:7], v[84:85] op_sel_hi:[1,0]
	v_pk_mul_f32 v[4:5], v[8:9], v[84:85] op_sel_hi:[1,0]
	v_cvt_pk_bf16_f32 v2, v2, v3
	v_cvt_pk_bf16_f32 v3, v4, v5
	v_pk_mul_f32 v[4:5], v[74:75], v[84:85] op_sel_hi:[1,0]
	v_pk_mul_f32 v[6:7], v[76:77], v[84:85] op_sel_hi:[1,0]
	v_cvt_pk_bf16_f32 v4, v4, v5
	v_cvt_pk_bf16_f32 v5, v6, v7
	v_pk_mul_f32 v[6:7], v[10:11], v[84:85] op_sel_hi:[1,0]
	v_pk_mul_f32 v[8:9], v[12:13], v[84:85] op_sel_hi:[1,0]
	v_cvt_pk_bf16_f32 v6, v6, v7
	v_cvt_pk_bf16_f32 v7, v8, v9
	v_pk_mul_f32 v[8:9], v[14:15], v[84:85] op_sel_hi:[1,0]
	v_pk_mul_f32 v[10:11], v[16:17], v[84:85] op_sel_hi:[1,0]
	v_cvt_pk_bf16_f32 v8, v8, v9
	v_cvt_pk_bf16_f32 v9, v10, v11
	v_pk_mul_f32 v[10:11], v[18:19], v[84:85] op_sel_hi:[1,0]
	v_pk_mul_f32 v[12:13], v[20:21], v[84:85] op_sel_hi:[1,0]
	v_cvt_pk_bf16_f32 v10, v10, v11
	v_cvt_pk_bf16_f32 v11, v12, v13
	v_pk_mul_f32 v[12:13], v[22:23], v[84:85] op_sel_hi:[1,0]
	v_pk_mul_f32 v[14:15], v[24:25], v[84:85] op_sel_hi:[1,0]
	v_cvt_pk_bf16_f32 v12, v12, v13
	v_cvt_pk_bf16_f32 v13, v14, v15
	v_pk_mul_f32 v[14:15], v[26:27], v[84:85] op_sel_hi:[1,0]
	v_pk_mul_f32 v[16:17], v[28:29], v[84:85] op_sel_hi:[1,0]
	v_cvt_pk_bf16_f32 v14, v14, v15
	v_cvt_pk_bf16_f32 v15, v16, v17
	v_pk_mul_f32 v[16:17], v[30:31], v[84:85] op_sel_hi:[1,0]
	v_pk_mul_f32 v[18:19], v[32:33], v[84:85] op_sel_hi:[1,0]
	v_cvt_pk_bf16_f32 v16, v16, v17
	v_cvt_pk_bf16_f32 v17, v18, v19
	v_pk_mul_f32 v[18:19], v[34:35], v[84:85] op_sel_hi:[1,0]
	v_pk_mul_f32 v[20:21], v[36:37], v[84:85] op_sel_hi:[1,0]
	v_cvt_pk_bf16_f32 v18, v18, v19
	v_cvt_pk_bf16_f32 v19, v20, v21
	v_pk_mul_f32 v[20:21], v[38:39], v[84:85] op_sel_hi:[1,0]
	v_pk_mul_f32 v[22:23], v[40:41], v[84:85] op_sel_hi:[1,0]
	v_cvt_pk_bf16_f32 v20, v20, v21
	v_cvt_pk_bf16_f32 v21, v22, v23
	v_pk_mul_f32 v[22:23], v[42:43], v[84:85] op_sel_hi:[1,0]
	v_pk_mul_f32 v[24:25], v[44:45], v[84:85] op_sel_hi:[1,0]
	v_cvt_pk_bf16_f32 v22, v22, v23
	v_cvt_pk_bf16_f32 v23, v24, v25
	v_pk_mul_f32 v[24:25], v[46:47], v[84:85] op_sel_hi:[1,0]
	v_pk_mul_f32 v[26:27], v[48:49], v[84:85] op_sel_hi:[1,0]
	v_cvt_pk_bf16_f32 v24, v24, v25
	v_cvt_pk_bf16_f32 v25, v26, v27
	v_pk_mul_f32 v[26:27], v[50:51], v[84:85] op_sel_hi:[1,0]
	v_pk_mul_f32 v[28:29], v[52:53], v[84:85] op_sel_hi:[1,0]
	v_cvt_pk_bf16_f32 v26, v26, v27
	v_cvt_pk_bf16_f32 v27, v28, v29
	v_pk_mul_f32 v[28:29], v[54:55], v[84:85] op_sel_hi:[1,0]
	v_pk_mul_f32 v[30:31], v[56:57], v[84:85] op_sel_hi:[1,0]
	s_add_u32 s24, s22, 0xf000400
	v_cvt_pk_bf16_f32 v28, v28, v29
	v_cvt_pk_bf16_f32 v29, v30, v31
	v_pk_mul_f32 v[30:31], v[58:59], v[84:85] op_sel_hi:[1,0]
	v_pk_mul_f32 v[32:33], v[60:61], v[84:85] op_sel_hi:[1,0]
	s_addc_u32 s25, s23, 0
	s_add_i32 s21, s21, s43
	v_cvt_pk_bf16_f32 v30, v30, v31
	v_cvt_pk_bf16_f32 v31, v32, v33
	v_pk_mul_f32 v[32:33], v[62:63], v[84:85] op_sel_hi:[1,0]
	v_pk_mul_f32 v[34:35], v[64:65], v[84:85] op_sel_hi:[1,0]
	v_add_u32_e32 v40, s21, v180
	v_cvt_pk_bf16_f32 v32, v32, v33
	v_cvt_pk_bf16_f32 v33, v34, v35
	v_lshlrev_b32_e32 v34, 6, v190
	v_mad_i64_i32 v[46:47], s[26:27], v40, s39, v[104:105]
	v_lshlrev_b32_e32 v40, 2, v40
	v_and_b32_e32 v50, 0x3c0, v34
	v_lshlrev_b32_e32 v34, 2, v190
	v_lshl_add_u64 v[38:39], s[24:25], 0, v[72:73]
	v_and_b32_e32 v52, 32, v40
	s_add_u32 s22, s22, 0xf000000
	v_and_b32_e32 v51, 32, v34
	v_lshl_add_u64 v[34:35], s[24:25], 0, v[90:91]
	v_and_or_b32 v38, v70, 24, v38
	v_add_u32_e32 v90, v184, v52
	s_addc_u32 s23, s23, 0
	v_mov_b32_e32 v67, v91
	v_mov_b32_e32 v71, v91
	v_and_b32_e32 v68, 0x1fc000, v68
	v_mov_b32_e32 v69, v91
	v_mov_b32_e32 v79, v91
	v_mov_b32_e32 v81, v91
	v_lshl_add_u64 v[38:39], v[38:39], 0, v[90:91]
	v_lshl_add_u64 v[48:49], s[22:23], 0, v[82:83]
	v_add_u32_e32 v90, v188, v52
	s_mov_b32 s20, 16
	v_lshl_add_u64 v[36:37], v[46:47], 0, v[66:67]
	v_lshl_add_u64 v[40:41], v[46:47], 0, v[70:71]
	v_lshl_add_u64 v[42:43], s[22:23], 0, v[68:69]
	v_lshl_add_u64 v[44:45], v[46:47], 0, v[78:79]
	v_lshl_add_u64 v[46:47], v[46:47], 0, v[80:81]
	v_lshl_add_u64 v[48:49], v[48:49], 0, v[90:91]
	v_mov_b32_e32 v52, v107
	v_lshl_add_u64 v[234:235], s[92:93], 0, v[46:47]
	global_load_dwordx2 v[200:201], v[234:235], off
	global_load_dwordx2 v[208:209], v[234:235], off offset:128
	global_load_dwordx2 v[216:217], v[234:235], off offset:256
	global_load_dwordx2 v[224:225], v[234:235], off offset:384
	v_lshl_add_u64 v[234:235], s[92:93], 0, v[44:45]
	global_load_dwordx2 v[202:203], v[234:235], off
	global_load_dwordx2 v[210:211], v[234:235], off offset:128
	global_load_dwordx2 v[218:219], v[234:235], off offset:256
	global_load_dwordx2 v[226:227], v[234:235], off offset:384
	v_lshl_add_u64 v[234:235], s[92:93], 0, v[40:41]
	global_load_dwordx2 v[204:205], v[234:235], off
	global_load_dwordx2 v[212:213], v[234:235], off offset:128
	global_load_dwordx2 v[220:221], v[234:235], off offset:256
	global_load_dwordx2 v[228:229], v[234:235], off offset:384
	v_lshl_add_u64 v[234:235], s[92:93], 0, v[36:37]
	global_load_dwordx2 v[206:207], v[234:235], off
	global_load_dwordx2 v[214:215], v[234:235], off offset:128
	global_load_dwordx2 v[222:223], v[234:235], off offset:256
	global_load_dwordx2 v[230:231], v[234:235], off offset:384
	s_barrier
